# GEMM K-loops: four load phases merged into two and 16-MFMA blocks into 32-MFMA blocks (8 barriers per K-tile pair instead of 16), uniform vmcnt(8); cold-start prologue wait vmcnt(2)
# speedup vs baseline: 1.0080x; 1.0080x over previous
.LBB0_57:
	s_add_u32 s20, s20, 0x80
	v_add_u32_e32 v12, 0x18000, v135
	s_addc_u32 s21, s21, 0
	v_readfirstlane_b32 s7, v12
	v_mov_b32_e32 v133, v177
	v_lshl_add_u64 v[10:11], s[20:21], 0, v[176:177]
	s_mov_b32 m0, s7
	v_add_u32_e32 v12, 0x1a000, v135
	s_waitcnt vmcnt(2)
	s_barrier
	global_load_lds_dwordx4 v[10:11], off
	v_lshl_add_u64 v[10:11], s[20:21], 0, v[132:133]
	v_readfirstlane_b32 s7, v12
	s_add_u32 s20, s28, 0x80
	v_add_u32_e32 v12, 0x8000, v135
	v_mov_b32_e32 v131, v177
	s_mov_b32 m0, s7
	s_addc_u32 s21, s29, 0
	v_readfirstlane_b32 s7, v12
	v_mov_b32_e32 v129, v177
	global_load_lds_dwordx4 v[10:11], off
	v_lshl_add_u64 v[10:11], s[20:21], 0, v[130:131]
	s_mov_b32 m0, s7
	v_add_u32_e32 v12, 0xa000, v135
	global_load_lds_dwordx4 v[10:11], off
	v_lshl_add_u64 v[10:11], s[20:21], 0, v[128:129]
	v_readfirstlane_b32 s7, v12
	s_add_u32 s20, s26, 0x80
	v_add_u32_e32 v12, 0x1c000, v135
	s_mov_b32 m0, s7
	s_addc_u32 s21, s27, 0
	v_readfirstlane_b32 s7, v12
	v_add_u32_e32 v12, 0x1e000, v135
	global_load_lds_dwordx4 v[10:11], off
	v_lshl_add_u64 v[10:11], s[20:21], 0, v[176:177]
	s_mov_b32 m0, s7
	v_readfirstlane_b32 s7, v12
	global_load_lds_dwordx4 v[10:11], off
	v_lshl_add_u64 v[10:11], s[20:21], 0, v[132:133]
	s_mov_b32 m0, s7
	s_nop 0
	global_load_lds_dwordx4 v[10:11], off
	s_waitcnt vmcnt(6)
	s_barrier
	s_branch .LBB0_62

.LBB0_63:
	ds_read_b128 v[150:153], v149 offset:0
	ds_read_b128 v[158:161], v149 offset:1024
	ds_read_b128 v[162:165], v149 offset:2048
	ds_read_b128 v[166:169], v149 offset:3072
	s_add_u32 s37, s7, s14
	s_addc_u32 s39, s20, s15
	s_add_u32 s38, s37, 0x80
	v_add_u32_e32 v156, 0xc000, v135
	s_addc_u32 s39, s39, 0
	v_readfirstlane_b32 s37, v156
	v_add_u32_e32 v157, 0xe000, v135
	v_lshl_add_u64 v[154:155], s[38:39], 0, v[130:131]
	s_mov_b32 m0, s37
	v_readfirstlane_b32 s37, v157
	ds_read_b128 v[170:173], v148 offset:0
	ds_read_b128 v[178:181], v148 offset:1024
	ds_read_b128 v[182:185], v148 offset:2048
	ds_read_b128 v[186:189], v148 offset:3072
	ds_read_b128 v[190:193], v148 offset:4096
	ds_read_b128 v[194:197], v148 offset:5120
	ds_read_b128 v[198:201], v148 offset:6144
	ds_read_b128 v[202:205], v148 offset:7168
	global_load_lds_dwordx4 v[154:155], off
	v_lshl_add_u64 v[154:155], s[38:39], 0, v[128:129]
	s_mov_b32 m0, s37
	s_nop 0
	global_load_lds_dwordx4 v[154:155], off
	ds_read_b128 v[206:209], v147 offset:0
	ds_read_b128 v[210:213], v147 offset:1024
	ds_read_b128 v[214:217], v147 offset:2048
	ds_read_b128 v[218:221], v147 offset:3072
	s_waitcnt vmcnt(8)
	s_waitcnt lgkmcnt(0)
	s_barrier
	s_waitcnt lgkmcnt(0)
	s_waitcnt lgkmcnt(0)
	s_setprio 1
	v_mfma_f32_16x16x32_bf16 v[124:127], v[150:153], v[170:173], v[124:127]
	v_mfma_f32_16x16x32_bf16 v[120:123], v[162:165], v[170:173], v[120:123]
	v_mfma_f32_16x16x32_bf16 v[116:119], v[150:153], v[182:185], v[116:119]
	v_mfma_f32_16x16x32_bf16 v[112:115], v[162:165], v[182:185], v[112:115]
	v_mfma_f32_16x16x32_bf16 v[108:111], v[150:153], v[190:193], v[108:111]
	v_mfma_f32_16x16x32_bf16 v[104:107], v[162:165], v[190:193], v[104:107]
	v_mfma_f32_16x16x32_bf16 v[100:103], v[150:153], v[198:201], v[100:103]
	v_mfma_f32_16x16x32_bf16 v[96:99], v[162:165], v[198:201], v[96:99]
	v_mfma_f32_16x16x32_bf16 v[124:127], v[158:161], v[178:181], v[124:127]
	v_mfma_f32_16x16x32_bf16 v[120:123], v[166:169], v[178:181], v[120:123]
	v_mfma_f32_16x16x32_bf16 v[116:119], v[158:161], v[186:189], v[116:119]
	v_mfma_f32_16x16x32_bf16 v[112:115], v[166:169], v[186:189], v[112:115]
	v_mfma_f32_16x16x32_bf16 v[108:111], v[158:161], v[194:197], v[108:111]
	v_mfma_f32_16x16x32_bf16 v[104:107], v[166:169], v[194:197], v[104:107]
	v_mfma_f32_16x16x32_bf16 v[100:103], v[158:161], v[202:205], v[100:103]
	v_mfma_f32_16x16x32_bf16 v[96:99], v[166:169], v[202:205], v[96:99]
	s_setprio 0
	s_waitcnt lgkmcnt(0)
	s_setprio 1
	v_mfma_f32_16x16x32_bf16 v[92:95], v[206:209], v[170:173], v[92:95]
	v_mfma_f32_16x16x32_bf16 v[88:91], v[214:217], v[170:173], v[88:91]
	v_mfma_f32_16x16x32_bf16 v[84:87], v[206:209], v[182:185], v[84:87]
	v_mfma_f32_16x16x32_bf16 v[80:83], v[214:217], v[182:185], v[80:83]
	v_mfma_f32_16x16x32_bf16 v[76:79], v[206:209], v[190:193], v[76:79]
	v_mfma_f32_16x16x32_bf16 v[72:75], v[214:217], v[190:193], v[72:75]
	v_mfma_f32_16x16x32_bf16 v[68:71], v[206:209], v[198:201], v[68:71]
	v_mfma_f32_16x16x32_bf16 v[64:67], v[214:217], v[198:201], v[64:67]
	v_mfma_f32_16x16x32_bf16 v[92:95], v[210:213], v[178:181], v[92:95]
	v_mfma_f32_16x16x32_bf16 v[88:91], v[218:221], v[178:181], v[88:91]
	v_mfma_f32_16x16x32_bf16 v[84:87], v[210:213], v[186:189], v[84:87]
	v_mfma_f32_16x16x32_bf16 v[80:83], v[218:221], v[186:189], v[80:83]
	v_mfma_f32_16x16x32_bf16 v[76:79], v[210:213], v[194:197], v[76:79]
	v_mfma_f32_16x16x32_bf16 v[72:75], v[218:221], v[194:197], v[72:75]
	v_mfma_f32_16x16x32_bf16 v[68:71], v[210:213], v[202:205], v[68:71]
	v_mfma_f32_16x16x32_bf16 v[64:67], v[218:221], v[202:205], v[64:67]
	s_setprio 0
	s_barrier
	s_add_u32 s37, s21, s14
	s_addc_u32 s40, s26, s15
	s_add_u32 s38, s37, 0x100
	s_addc_u32 s39, s40, 0
	v_readfirstlane_b32 s41, v141
	v_lshl_add_u64 v[154:155], s[38:39], 0, v[176:177]
	s_mov_b32 m0, s41
	s_nop 0
	global_load_lds_dwordx4 v[154:155], off
	v_lshl_add_u64 v[154:155], s[38:39], 0, v[132:133]
	v_readfirstlane_b32 s38, v140
	s_mov_b32 m0, s38
	s_nop 0
	global_load_lds_dwordx4 v[154:155], off
	s_add_u32 s41, s2, s14
	s_addc_u32 s42, s3, s15
	s_add_u32 s38, s41, 0x100
	s_addc_u32 s39, s42, 0
	v_readfirstlane_b32 s43, v135
	v_lshl_add_u64 v[154:155], s[38:39], 0, v[130:131]
	s_mov_b32 m0, s43
	ds_read_b128 v[170:173], v146 offset:0
	ds_read_b128 v[178:181], v146 offset:1024
	ds_read_b128 v[182:185], v146 offset:2048
	ds_read_b128 v[186:189], v146 offset:3072
	ds_read_b128 v[190:193], v146 offset:4096
	ds_read_b128 v[194:197], v146 offset:5120
	ds_read_b128 v[198:201], v146 offset:6144
	ds_read_b128 v[202:205], v146 offset:7168
	global_load_lds_dwordx4 v[154:155], off
	v_lshl_add_u64 v[154:155], s[38:39], 0, v[128:129]
	v_readfirstlane_b32 s38, v136
	s_mov_b32 m0, s38
	s_nop 0
	global_load_lds_dwordx4 v[154:155], off
	s_add_u32 s43, s18, s14
	s_addc_u32 s44, s19, s15
	s_add_u32 s38, s43, 0x100
	s_addc_u32 s39, s44, 0
	v_readfirstlane_b32 s45, v139
	v_lshl_add_u64 v[226:227], s[38:39], 0, v[176:177]
	s_mov_b32 m0, s45
	s_nop 0
	global_load_lds_dwordx4 v[226:227], off
	v_lshl_add_u64 v[226:227], s[38:39], 0, v[132:133]
	v_readfirstlane_b32 s38, v138
	s_mov_b32 m0, s38
	s_nop 0
	global_load_lds_dwordx4 v[226:227], off
	s_waitcnt vmcnt(8)
	s_waitcnt lgkmcnt(0)
	s_barrier
	s_waitcnt lgkmcnt(0)
	s_setprio 1
	v_mfma_f32_16x16x32_bf16 v[60:63], v[150:153], v[170:173], v[60:63]
	v_mfma_f32_16x16x32_bf16 v[56:59], v[162:165], v[170:173], v[56:59]
	v_mfma_f32_16x16x32_bf16 v[52:55], v[150:153], v[182:185], v[52:55]
	v_mfma_f32_16x16x32_bf16 v[48:51], v[162:165], v[182:185], v[48:51]
	v_mfma_f32_16x16x32_bf16 v[44:47], v[150:153], v[190:193], v[44:47]
	v_mfma_f32_16x16x32_bf16 v[40:43], v[162:165], v[190:193], v[40:43]
	v_mfma_f32_16x16x32_bf16 v[36:39], v[150:153], v[198:201], v[36:39]
	v_mfma_f32_16x16x32_bf16 v[32:35], v[162:165], v[198:201], v[32:35]
	v_mfma_f32_16x16x32_bf16 v[60:63], v[158:161], v[178:181], v[60:63]
	v_mfma_f32_16x16x32_bf16 v[56:59], v[166:169], v[178:181], v[56:59]
	v_mfma_f32_16x16x32_bf16 v[52:55], v[158:161], v[186:189], v[52:55]
	v_mfma_f32_16x16x32_bf16 v[48:51], v[166:169], v[186:189], v[48:51]
	v_mfma_f32_16x16x32_bf16 v[44:47], v[158:161], v[194:197], v[44:47]
	v_mfma_f32_16x16x32_bf16 v[40:43], v[166:169], v[194:197], v[40:43]
	v_mfma_f32_16x16x32_bf16 v[36:39], v[158:161], v[202:205], v[36:39]
	v_mfma_f32_16x16x32_bf16 v[32:35], v[166:169], v[202:205], v[32:35]
	s_setprio 0
	s_setprio 1
	v_mfma_f32_16x16x32_bf16 v[28:31], v[206:209], v[170:173], v[28:31]
	v_mfma_f32_16x16x32_bf16 v[24:27], v[214:217], v[170:173], v[24:27]
	v_mfma_f32_16x16x32_bf16 v[20:23], v[206:209], v[182:185], v[20:23]
	v_mfma_f32_16x16x32_bf16 v[16:19], v[214:217], v[182:185], v[16:19]
	v_mfma_f32_16x16x32_bf16 v[12:15], v[206:209], v[190:193], v[12:15]
	v_mfma_f32_16x16x32_bf16 v[8:11], v[214:217], v[190:193], v[8:11]
	v_mfma_f32_16x16x32_bf16 v[4:7], v[206:209], v[198:201], v[4:7]
	v_mfma_f32_16x16x32_bf16 v[0:3], v[214:217], v[198:201], v[0:3]
	v_mfma_f32_16x16x32_bf16 v[28:31], v[210:213], v[178:181], v[28:31]
	v_mfma_f32_16x16x32_bf16 v[24:27], v[218:221], v[178:181], v[24:27]
	v_mfma_f32_16x16x32_bf16 v[20:23], v[210:213], v[186:189], v[20:23]
	v_mfma_f32_16x16x32_bf16 v[16:19], v[218:221], v[186:189], v[16:19]
	v_mfma_f32_16x16x32_bf16 v[12:15], v[210:213], v[194:197], v[12:15]
	v_mfma_f32_16x16x32_bf16 v[8:11], v[218:221], v[194:197], v[8:11]
	v_mfma_f32_16x16x32_bf16 v[4:7], v[210:213], v[202:205], v[4:7]
	v_mfma_f32_16x16x32_bf16 v[0:3], v[218:221], v[202:205], v[0:3]
	s_setprio 0
	s_barrier
	ds_read_b128 v[158:161], v145 offset:0
	ds_read_b128 v[162:165], v145 offset:1024
	ds_read_b128 v[166:169], v145 offset:2048
	ds_read_b128 v[170:173], v145 offset:3072
	s_add_u32 s38, s27, s14
	s_addc_u32 s39, s28, s15
	v_readfirstlane_b32 s45, v137
	v_lshl_add_u64 v[150:151], s[38:39], 0, v[130:131]
	s_mov_b32 m0, s45
	ds_read_b128 v[152:155], v144 offset:0
	ds_read_b128 v[178:181], v144 offset:1024
	ds_read_b128 v[182:185], v144 offset:2048
	ds_read_b128 v[186:189], v144 offset:3072
	ds_read_b128 v[190:193], v144 offset:4096
	ds_read_b128 v[194:197], v144 offset:5120
	ds_read_b128 v[198:201], v144 offset:6144
	ds_read_b128 v[202:205], v144 offset:7168
	s_nop 0
	global_load_lds_dwordx4 v[150:151], off
	v_lshl_add_u64 v[150:151], s[38:39], 0, v[128:129]
	v_readfirstlane_b32 s38, v134
	s_mov_b32 m0, s38
	s_nop 0
	global_load_lds_dwordx4 v[150:151], off
	ds_read_b128 v[206:209], v143 offset:0
	ds_read_b128 v[210:213], v143 offset:1024
	ds_read_b128 v[214:217], v143 offset:2048
	ds_read_b128 v[218:221], v143 offset:3072
	s_waitcnt vmcnt(8)
	s_waitcnt lgkmcnt(0)
	s_barrier
	s_waitcnt lgkmcnt(0)
	s_waitcnt lgkmcnt(0)
	s_setprio 1
	v_mfma_f32_16x16x32_bf16 v[124:127], v[158:161], v[152:155], v[124:127]
	v_mfma_f32_16x16x32_bf16 v[120:123], v[166:169], v[152:155], v[120:123]
	v_mfma_f32_16x16x32_bf16 v[116:119], v[158:161], v[182:185], v[116:119]
	v_mfma_f32_16x16x32_bf16 v[112:115], v[166:169], v[182:185], v[112:115]
	v_mfma_f32_16x16x32_bf16 v[108:111], v[158:161], v[190:193], v[108:111]
	v_mfma_f32_16x16x32_bf16 v[104:107], v[166:169], v[190:193], v[104:107]
	v_mfma_f32_16x16x32_bf16 v[100:103], v[158:161], v[198:201], v[100:103]
	v_mfma_f32_16x16x32_bf16 v[96:99], v[166:169], v[198:201], v[96:99]
	v_mfma_f32_16x16x32_bf16 v[124:127], v[162:165], v[178:181], v[124:127]
	v_mfma_f32_16x16x32_bf16 v[120:123], v[170:173], v[178:181], v[120:123]
	v_mfma_f32_16x16x32_bf16 v[116:119], v[162:165], v[186:189], v[116:119]
	v_mfma_f32_16x16x32_bf16 v[112:115], v[170:173], v[186:189], v[112:115]
	v_mfma_f32_16x16x32_bf16 v[108:111], v[162:165], v[194:197], v[108:111]
	v_mfma_f32_16x16x32_bf16 v[104:107], v[170:173], v[194:197], v[104:107]
	v_mfma_f32_16x16x32_bf16 v[100:103], v[162:165], v[202:205], v[100:103]
	v_mfma_f32_16x16x32_bf16 v[96:99], v[170:173], v[202:205], v[96:99]
	s_setprio 0
	s_waitcnt lgkmcnt(0)
	s_setprio 1
	v_mfma_f32_16x16x32_bf16 v[92:95], v[206:209], v[152:155], v[92:95]
	v_mfma_f32_16x16x32_bf16 v[88:91], v[214:217], v[152:155], v[88:91]
	v_mfma_f32_16x16x32_bf16 v[84:87], v[206:209], v[182:185], v[84:87]
	v_mfma_f32_16x16x32_bf16 v[80:83], v[214:217], v[182:185], v[80:83]
	v_mfma_f32_16x16x32_bf16 v[76:79], v[206:209], v[190:193], v[76:79]
	v_mfma_f32_16x16x32_bf16 v[72:75], v[214:217], v[190:193], v[72:75]
	v_mfma_f32_16x16x32_bf16 v[68:71], v[206:209], v[198:201], v[68:71]
	v_mfma_f32_16x16x32_bf16 v[64:67], v[214:217], v[198:201], v[64:67]
	v_mfma_f32_16x16x32_bf16 v[92:95], v[210:213], v[178:181], v[92:95]
	v_mfma_f32_16x16x32_bf16 v[88:91], v[218:221], v[178:181], v[88:91]
	v_mfma_f32_16x16x32_bf16 v[84:87], v[210:213], v[186:189], v[84:87]
	v_mfma_f32_16x16x32_bf16 v[80:83], v[218:221], v[186:189], v[80:83]
	v_mfma_f32_16x16x32_bf16 v[76:79], v[210:213], v[194:197], v[76:79]
	v_mfma_f32_16x16x32_bf16 v[72:75], v[218:221], v[194:197], v[72:75]
	v_mfma_f32_16x16x32_bf16 v[68:71], v[210:213], v[202:205], v[68:71]
	v_mfma_f32_16x16x32_bf16 v[64:67], v[218:221], v[202:205], v[64:67]
	s_setprio 0
	s_barrier
	s_add_u32 s38, s37, 0x180
	v_add_u32_e32 v150, 0x18000, v135
	s_addc_u32 s39, s40, 0
	v_readfirstlane_b32 s37, v150
	v_add_u32_e32 v151, 0x1a000, v135
	v_lshl_add_u64 v[174:175], s[38:39], 0, v[176:177]
	s_mov_b32 m0, s37
	v_readfirstlane_b32 s37, v151
	global_load_lds_dwordx4 v[174:175], off
	v_lshl_add_u64 v[174:175], s[38:39], 0, v[132:133]
	s_mov_b32 m0, s37
	s_nop 0
	global_load_lds_dwordx4 v[174:175], off
	s_add_u32 s38, s41, 0x180
	v_add_u32_e32 v152, 0x8000, v135
	s_addc_u32 s39, s42, 0
	v_readfirstlane_b32 s37, v152
	v_add_u32_e32 v153, 0xa000, v135
	v_lshl_add_u64 v[154:155], s[38:39], 0, v[130:131]
	s_mov_b32 m0, s37
	v_readfirstlane_b32 s37, v153
	ds_read_b128 v[178:181], v142 offset:0
	ds_read_b128 v[182:185], v142 offset:1024
	ds_read_b128 v[186:189], v142 offset:2048
	ds_read_b128 v[190:193], v142 offset:3072
	ds_read_b128 v[194:197], v142 offset:4096
	ds_read_b128 v[198:201], v142 offset:5120
	ds_read_b128 v[202:205], v142 offset:6144
	ds_read_b128 v[222:225], v142 offset:7168
	global_load_lds_dwordx4 v[154:155], off
	v_lshl_add_u64 v[154:155], s[38:39], 0, v[128:129]
	s_mov_b32 m0, s37
	s_nop 0
	global_load_lds_dwordx4 v[154:155], off
	s_add_u32 s38, s43, 0x180
	v_add_u32_e32 v154, 0x1c000, v135
	s_addc_u32 s39, s44, 0
	v_readfirstlane_b32 s37, v154
	v_add_u32_e32 v155, 0x1e000, v135
	v_lshl_add_u64 v[226:227], s[38:39], 0, v[176:177]
	s_mov_b32 m0, s37
	v_readfirstlane_b32 s37, v155
	global_load_lds_dwordx4 v[226:227], off
	v_lshl_add_u64 v[226:227], s[38:39], 0, v[132:133]
	s_mov_b32 m0, s37
	s_nop 0
	global_load_lds_dwordx4 v[226:227], off
	s_waitcnt vmcnt(8)
	s_waitcnt lgkmcnt(0)
	s_barrier
	s_waitcnt lgkmcnt(0)
	s_setprio 1
	v_mfma_f32_16x16x32_bf16 v[60:63], v[158:161], v[178:181], v[60:63]
	v_mfma_f32_16x16x32_bf16 v[56:59], v[166:169], v[178:181], v[56:59]
	v_mfma_f32_16x16x32_bf16 v[52:55], v[158:161], v[186:189], v[52:55]
	v_mfma_f32_16x16x32_bf16 v[48:51], v[166:169], v[186:189], v[48:51]
	v_mfma_f32_16x16x32_bf16 v[44:47], v[158:161], v[194:197], v[44:47]
	v_mfma_f32_16x16x32_bf16 v[40:43], v[166:169], v[194:197], v[40:43]
	v_mfma_f32_16x16x32_bf16 v[36:39], v[158:161], v[202:205], v[36:39]
	v_mfma_f32_16x16x32_bf16 v[32:35], v[166:169], v[202:205], v[32:35]
	v_mfma_f32_16x16x32_bf16 v[60:63], v[162:165], v[182:185], v[60:63]
	v_mfma_f32_16x16x32_bf16 v[56:59], v[170:173], v[182:185], v[56:59]
	v_mfma_f32_16x16x32_bf16 v[52:55], v[162:165], v[190:193], v[52:55]
	v_mfma_f32_16x16x32_bf16 v[48:51], v[170:173], v[190:193], v[48:51]
	v_mfma_f32_16x16x32_bf16 v[44:47], v[162:165], v[198:201], v[44:47]
	v_mfma_f32_16x16x32_bf16 v[40:43], v[170:173], v[198:201], v[40:43]
	v_mfma_f32_16x16x32_bf16 v[36:39], v[162:165], v[222:225], v[36:39]
	v_mfma_f32_16x16x32_bf16 v[32:35], v[170:173], v[222:225], v[32:35]
	s_setprio 0
	s_setprio 1
	v_mfma_f32_16x16x32_bf16 v[28:31], v[206:209], v[178:181], v[28:31]
	v_mfma_f32_16x16x32_bf16 v[24:27], v[214:217], v[178:181], v[24:27]
	v_mfma_f32_16x16x32_bf16 v[20:23], v[206:209], v[186:189], v[20:23]
	v_mfma_f32_16x16x32_bf16 v[16:19], v[214:217], v[186:189], v[16:19]
	v_mfma_f32_16x16x32_bf16 v[12:15], v[206:209], v[194:197], v[12:15]
	v_mfma_f32_16x16x32_bf16 v[8:11], v[214:217], v[194:197], v[8:11]
	v_mfma_f32_16x16x32_bf16 v[4:7], v[206:209], v[202:205], v[4:7]
	v_mfma_f32_16x16x32_bf16 v[0:3], v[214:217], v[202:205], v[0:3]
	v_mfma_f32_16x16x32_bf16 v[28:31], v[210:213], v[182:185], v[28:31]
	v_mfma_f32_16x16x32_bf16 v[24:27], v[218:221], v[182:185], v[24:27]
	v_mfma_f32_16x16x32_bf16 v[20:23], v[210:213], v[190:193], v[20:23]
	v_mfma_f32_16x16x32_bf16 v[16:19], v[218:221], v[190:193], v[16:19]
	v_mfma_f32_16x16x32_bf16 v[12:15], v[210:213], v[198:201], v[12:15]
	v_mfma_f32_16x16x32_bf16 v[8:11], v[218:221], v[198:201], v[8:11]
	v_mfma_f32_16x16x32_bf16 v[4:7], v[210:213], v[222:225], v[4:7]
	v_mfma_f32_16x16x32_bf16 v[0:3], v[218:221], v[222:225], v[0:3]
	s_setprio 0
	s_add_i32 s29, s29, 2
	s_add_u32 s14, s14, 0x100
	s_addc_u32 s15, s15, 0
	s_cmp_gt_u32 s29, 11
	s_barrier
	s_cbranch_scc0 .LBB0_63
	v_add_u32_e32 v156, 0xc000, v135
	v_add_u32_e32 v157, 0xe000, v135
	v_add_u32_e32 v150, 0x18000, v135
	v_add_u32_e32 v151, 0x1a000, v135
	v_add_u32_e32 v152, 0x8000, v135
	v_add_u32_e32 v153, 0xa000, v135
	v_add_u32_e32 v154, 0x1c000, v135
	v_add_u32_e32 v155, 0x1e000, v135
	s_add_u32 s2, s7, 0x780
	s_addc_u32 s3, s20, 0
	v_readfirstlane_b32 s7, v156
	ds_read_b128 v[158:161], v149 offset:0
	ds_read_b128 v[162:165], v149 offset:1024
	ds_read_b128 v[166:169], v149 offset:2048
	ds_read_b128 v[170:173], v149 offset:3072
	ds_read_b128 v[178:181], v148 offset:0
	ds_read_b128 v[182:185], v148 offset:1024
	ds_read_b128 v[186:189], v148 offset:2048
	ds_read_b128 v[190:193], v148 offset:3072
	ds_read_b128 v[194:197], v148 offset:4096
	ds_read_b128 v[198:201], v148 offset:5120
	ds_read_b128 v[202:205], v148 offset:6144
	ds_read_b128 v[206:209], v148 offset:7168
	v_lshl_add_u64 v[148:149], s[2:3], 0, v[130:131]
	s_mov_b32 m0, s7
	s_nop 0
	global_load_lds_dwordx4 v[148:149], off
	v_lshl_add_u64 v[148:149], s[2:3], 0, v[128:129]
	v_readfirstlane_b32 s2, v157
	s_mov_b32 m0, s2
	s_nop 0
	global_load_lds_dwordx4 v[148:149], off
	s_waitcnt vmcnt(10)
	s_barrier
	s_waitcnt lgkmcnt(0)
	s_waitcnt lgkmcnt(0)
	s_setprio 1
	v_mfma_f32_16x16x32_bf16 v[124:127], v[158:161], v[178:181], v[124:127]
	v_mfma_f32_16x16x32_bf16 v[120:123], v[166:169], v[178:181], v[120:123]
	v_mfma_f32_16x16x32_bf16 v[116:119], v[158:161], v[186:189], v[116:119]
	v_mfma_f32_16x16x32_bf16 v[112:115], v[166:169], v[186:189], v[112:115]
	v_mfma_f32_16x16x32_bf16 v[100:103], v[158:161], v[202:205], v[100:103]
	v_mfma_f32_16x16x32_bf16 v[96:99], v[166:169], v[202:205], v[96:99]
	v_mfma_f32_16x16x32_bf16 v[124:127], v[162:165], v[182:185], v[124:127]
	v_mfma_f32_16x16x32_bf16 v[120:123], v[170:173], v[182:185], v[120:123]
	v_mfma_f32_16x16x32_bf16 v[116:119], v[162:165], v[190:193], v[116:119]
	v_mfma_f32_16x16x32_bf16 v[112:115], v[170:173], v[190:193], v[112:115]
	v_mfma_f32_16x16x32_bf16 v[108:111], v[158:161], v[194:197], v[108:111]
	v_mfma_f32_16x16x32_bf16 v[104:107], v[166:169], v[194:197], v[104:107]
	v_mfma_f32_16x16x32_bf16 v[100:103], v[162:165], v[206:209], v[100:103]
	v_mfma_f32_16x16x32_bf16 v[96:99], v[170:173], v[206:209], v[96:99]
	v_mfma_f32_16x16x32_bf16 v[210:213], v[162:165], v[198:201], v[108:111]
	v_mfma_f32_16x16x32_bf16 v[214:217], v[170:173], v[198:201], v[104:107]
	s_setprio 0
	s_barrier
	ds_read_b128 v[104:107], v147 offset:0
	ds_read_b128 v[108:111], v147 offset:1024
	ds_read_b128 v[218:221], v147 offset:2048
	ds_read_b128 v[222:225], v147 offset:3072
	s_waitcnt vmcnt(8)
	s_barrier
	s_waitcnt lgkmcnt(0)
	s_setprio 1
	v_mfma_f32_16x16x32_bf16 v[92:95], v[104:107], v[178:181], v[92:95]
	v_mfma_f32_16x16x32_bf16 v[88:91], v[218:221], v[178:181], v[88:91]
	v_mfma_f32_16x16x32_bf16 v[76:79], v[104:107], v[194:197], v[76:79]
	v_mfma_f32_16x16x32_bf16 v[72:75], v[218:221], v[194:197], v[72:75]
	v_mfma_f32_16x16x32_bf16 v[68:71], v[104:107], v[202:205], v[68:71]
	v_mfma_f32_16x16x32_bf16 v[92:95], v[108:111], v[182:185], v[92:95]
	v_mfma_f32_16x16x32_bf16 v[88:91], v[222:225], v[182:185], v[88:91]
	v_mfma_f32_16x16x32_bf16 v[84:87], v[104:107], v[186:189], v[84:87]
	v_mfma_f32_16x16x32_bf16 v[80:83], v[218:221], v[186:189], v[80:83]
	v_mfma_f32_16x16x32_bf16 v[76:79], v[108:111], v[198:201], v[76:79]
	v_mfma_f32_16x16x32_bf16 v[72:75], v[222:225], v[198:201], v[72:75]
	v_mfma_f32_16x16x32_bf16 v[68:71], v[108:111], v[206:209], v[68:71]
	v_mfma_f32_16x16x32_bf16 v[64:67], v[218:221], v[202:205], v[64:67]
	v_mfma_f32_16x16x32_bf16 v[178:181], v[108:111], v[190:193], v[84:87]
	v_mfma_f32_16x16x32_bf16 v[182:185], v[222:225], v[190:193], v[80:83]
	v_mfma_f32_16x16x32_bf16 v[186:189], v[222:225], v[206:209], v[64:67]
	s_setprio 0
	s_barrier
	ds_read_b128 v[64:67], v146 offset:0
	ds_read_b128 v[80:83], v146 offset:1024
	ds_read_b128 v[84:87], v146 offset:2048
	ds_read_b128 v[190:193], v146 offset:3072
	ds_read_b128 v[194:197], v146 offset:4096
	ds_read_b128 v[198:201], v146 offset:5120
	ds_read_b128 v[202:205], v146 offset:6144
	ds_read_b128 v[146:149], v146 offset:7168
	s_waitcnt vmcnt(4)
	s_barrier
	s_waitcnt lgkmcnt(0)
	s_setprio 1
	s_nop 0
	v_mfma_f32_16x16x32_bf16 v[60:63], v[158:161], v[64:67], v[60:63]
	v_mfma_f32_16x16x32_bf16 v[56:59], v[166:169], v[64:67], v[56:59]
	v_mfma_f32_16x16x32_bf16 v[60:63], v[162:165], v[80:83], v[60:63]
	v_mfma_f32_16x16x32_bf16 v[56:59], v[170:173], v[80:83], v[56:59]
	v_mfma_f32_16x16x32_bf16 v[52:55], v[158:161], v[84:87], v[52:55]
	v_mfma_f32_16x16x32_bf16 v[48:51], v[166:169], v[84:87], v[48:51]
	v_mfma_f32_16x16x32_bf16 v[44:47], v[158:161], v[194:197], v[44:47]
	v_mfma_f32_16x16x32_bf16 v[40:43], v[166:169], v[194:197], v[40:43]
	v_mfma_f32_16x16x32_bf16 v[36:39], v[158:161], v[202:205], v[36:39]
	v_mfma_f32_16x16x32_bf16 v[32:35], v[166:169], v[202:205], v[32:35]
	v_mfma_f32_16x16x32_bf16 v[206:209], v[162:165], v[190:193], v[52:55]
	v_mfma_f32_16x16x32_bf16 v[226:229], v[170:173], v[190:193], v[48:51]
	v_mfma_f32_16x16x32_bf16 v[232:235], v[162:165], v[198:201], v[44:47]
	v_mfma_f32_16x16x32_bf16 v[238:241], v[170:173], v[198:201], v[40:43]
	v_mfma_f32_16x16x32_bf16 v[156:159], v[162:165], v[146:149], v[36:39]
	v_mfma_f32_16x16x32_bf16 v[160:163], v[170:173], v[146:149], v[32:35]
	s_setprio 0
	s_setprio 1
	v_mfma_f32_16x16x32_bf16 v[28:31], v[104:107], v[64:67], v[28:31]
	v_mfma_f32_16x16x32_bf16 v[24:27], v[218:221], v[64:67], v[24:27]
	v_mfma_f32_16x16x32_bf16 v[12:15], v[104:107], v[194:197], v[12:15]
	v_mfma_f32_16x16x32_bf16 v[8:11], v[218:221], v[194:197], v[8:11]
	v_mfma_f32_16x16x32_bf16 v[28:31], v[108:111], v[80:83], v[28:31]
	v_mfma_f32_16x16x32_bf16 v[24:27], v[222:225], v[80:83], v[24:27]
	v_mfma_f32_16x16x32_bf16 v[20:23], v[104:107], v[84:87], v[20:23]
	v_mfma_f32_16x16x32_bf16 v[16:19], v[218:221], v[84:87], v[16:19]
	v_mfma_f32_16x16x32_bf16 v[12:15], v[108:111], v[198:201], v[12:15]
	v_mfma_f32_16x16x32_bf16 v[8:11], v[222:225], v[198:201], v[8:11]
	v_mfma_f32_16x16x32_bf16 v[4:7], v[104:107], v[202:205], v[4:7]
	v_mfma_f32_16x16x32_bf16 v[0:3], v[218:221], v[202:205], v[0:3]
	v_mfma_f32_16x16x32_bf16 v[164:167], v[108:111], v[190:193], v[20:23]
	v_mfma_f32_16x16x32_bf16 v[168:171], v[222:225], v[190:193], v[16:19]
	v_mfma_f32_16x16x32_bf16 v[172:175], v[108:111], v[146:149], v[4:7]
	v_mfma_f32_16x16x32_bf16 v[146:149], v[222:225], v[146:149], v[0:3]
	s_setprio 0
	s_barrier
	ds_read_b128 v[0:3], v145 offset:0
	ds_read_b128 v[4:7], v145 offset:1024
	ds_read_b128 v[190:193], v145 offset:2048
	ds_read_b128 v[194:197], v145 offset:3072
	ds_read_b128 v[16:19], v144 offset:0
	ds_read_b128 v[20:23], v144 offset:1024
	ds_read_b128 v[40:43], v144 offset:2048
	ds_read_b128 v[44:47], v144 offset:3072
	ds_read_b128 v[64:67], v144 offset:4096
	ds_read_b128 v[198:201], v144 offset:5120
	ds_read_b128 v[202:205], v144 offset:6144
	ds_read_b128 v[218:221], v144 offset:7168
	s_waitcnt vmcnt(2)
	s_barrier
	s_waitcnt lgkmcnt(0)
	s_waitcnt lgkmcnt(0)
	s_setprio 1
	v_mfma_f32_16x16x32_bf16 v[32:35], v[0:3], v[16:19], v[124:127]
	v_mfma_f32_16x16x32_bf16 v[104:107], v[4:7], v[20:23], v[32:35]
	v_mfma_f32_16x16x32_bf16 v[32:35], v[190:193], v[16:19], v[120:123]
	v_mfma_f32_16x16x32_bf16 v[108:111], v[194:197], v[20:23], v[32:35]
	v_mfma_f32_16x16x32_bf16 v[32:35], v[0:3], v[40:43], v[116:119]
	v_mfma_f32_16x16x32_bf16 v[80:83], v[4:7], v[44:47], v[32:35]
	v_mfma_f32_16x16x32_bf16 v[32:35], v[190:193], v[40:43], v[112:115]
	v_mfma_f32_16x16x32_bf16 v[84:87], v[194:197], v[44:47], v[32:35]
	v_mfma_f32_16x16x32_bf16 v[32:35], v[0:3], v[64:67], v[210:213]
	v_mfma_f32_16x16x32_bf16 v[48:51], v[4:7], v[198:201], v[32:35]
	v_mfma_f32_16x16x32_bf16 v[32:35], v[190:193], v[64:67], v[214:217]
	v_mfma_f32_16x16x32_bf16 v[52:55], v[194:197], v[198:201], v[32:35]
	v_mfma_f32_16x16x32_bf16 v[32:35], v[0:3], v[202:205], v[100:103]
	v_mfma_f32_16x16x32_bf16 v[36:39], v[190:193], v[202:205], v[96:99]
	v_mfma_f32_16x16x32_bf16 v[32:35], v[4:7], v[218:221], v[32:35]
	v_mfma_f32_16x16x32_bf16 v[36:39], v[194:197], v[218:221], v[36:39]
	s_setprio 0
	s_barrier
	ds_read_b128 v[210:213], v143 offset:0
	ds_read_b128 v[214:217], v143 offset:1024
	ds_read_b128 v[222:225], v143 offset:2048
	ds_read_b128 v[242:245], v143 offset:3072
	s_waitcnt vmcnt(0)
	s_barrier
	s_waitcnt lgkmcnt(0)
	s_setprio 1
	v_mfma_f32_16x16x32_bf16 v[92:95], v[210:213], v[16:19], v[92:95]
	v_mfma_f32_16x16x32_bf16 v[16:19], v[222:225], v[16:19], v[88:91]
	v_mfma_f32_16x16x32_bf16 v[124:127], v[242:245], v[20:23], v[16:19]
	v_mfma_f32_16x16x32_bf16 v[16:19], v[210:213], v[40:43], v[178:181]
	v_mfma_f32_16x16x32_bf16 v[112:115], v[214:217], v[44:47], v[16:19]
	v_mfma_f32_16x16x32_bf16 v[16:19], v[222:225], v[40:43], v[182:185]
	v_mfma_f32_16x16x32_bf16 v[116:119], v[242:245], v[44:47], v[16:19]
	v_mfma_f32_16x16x32_bf16 v[16:19], v[210:213], v[64:67], v[76:79]
	v_mfma_f32_16x16x32_bf16 v[96:99], v[214:217], v[198:201], v[16:19]
	v_mfma_f32_16x16x32_bf16 v[16:19], v[222:225], v[64:67], v[72:75]
	v_mfma_f32_16x16x32_bf16 v[100:103], v[242:245], v[198:201], v[16:19]
	v_mfma_f32_16x16x32_bf16 v[16:19], v[210:213], v[202:205], v[68:71]
	v_mfma_f32_16x16x32_bf16 v[64:67], v[214:217], v[218:221], v[16:19]
	v_mfma_f32_16x16x32_bf16 v[16:19], v[222:225], v[202:205], v[186:189]
	v_mfma_f32_16x16x32_bf16 v[120:123], v[214:217], v[20:23], v[92:95]
	v_mfma_f32_16x16x32_bf16 v[68:71], v[242:245], v[218:221], v[16:19]
	s_setprio 0
	s_barrier
	ds_read_b128 v[92:95], v142 offset:0
	ds_read_b128 v[178:181], v142 offset:1024
	ds_read_b128 v[182:185], v142 offset:2048
	ds_read_b128 v[186:189], v142 offset:3072
	ds_read_b128 v[198:201], v142 offset:4096
	ds_read_b128 v[202:205], v142 offset:5120
	ds_read_b128 v[218:221], v142 offset:6144
	ds_read_b128 v[142:145], v142 offset:7168
	s_barrier
	s_waitcnt lgkmcnt(0)
	s_setprio 1
	v_mfma_f32_16x16x32_bf16 v[16:19], v[0:3], v[92:95], v[60:63]
	v_mfma_f32_16x16x32_bf16 v[72:75], v[4:7], v[178:181], v[16:19]
	v_mfma_f32_16x16x32_bf16 v[16:19], v[190:193], v[92:95], v[56:59]
	v_mfma_f32_16x16x32_bf16 v[76:79], v[194:197], v[178:181], v[16:19]
	v_mfma_f32_16x16x32_bf16 v[16:19], v[0:3], v[182:185], v[206:209]
	v_mfma_f32_16x16x32_bf16 v[40:43], v[4:7], v[186:189], v[16:19]
	v_mfma_f32_16x16x32_bf16 v[16:19], v[190:193], v[182:185], v[226:229]
	v_mfma_f32_16x16x32_bf16 v[44:47], v[194:197], v[186:189], v[16:19]
	v_mfma_f32_16x16x32_bf16 v[16:19], v[0:3], v[198:201], v[232:235]
	v_mfma_f32_16x16x32_bf16 v[0:3], v[0:3], v[218:221], v[156:159]
	v_mfma_f32_16x16x32_bf16 v[16:19], v[4:7], v[202:205], v[16:19]
	v_mfma_f32_16x16x32_bf16 v[20:23], v[190:193], v[198:201], v[238:241]
	v_mfma_f32_16x16x32_bf16 v[0:3], v[4:7], v[142:145], v[0:3]
	v_mfma_f32_16x16x32_bf16 v[4:7], v[190:193], v[218:221], v[160:163]
	v_mfma_f32_16x16x32_bf16 v[20:23], v[194:197], v[202:205], v[20:23]
	v_mfma_f32_16x16x32_bf16 v[4:7], v[194:197], v[142:145], v[4:7]
	s_setprio 0
	s_setprio 1
	v_mfma_f32_16x16x32_bf16 v[24:27], v[222:225], v[92:95], v[24:27]
	v_mfma_f32_16x16x32_bf16 v[28:31], v[210:213], v[92:95], v[28:31]
	v_mfma_f32_16x16x32_bf16 v[92:95], v[242:245], v[178:181], v[24:27]
	v_mfma_f32_16x16x32_bf16 v[24:27], v[210:213], v[182:185], v[164:167]
	v_mfma_f32_16x16x32_bf16 v[56:59], v[214:217], v[186:189], v[24:27]
	v_mfma_f32_16x16x32_bf16 v[24:27], v[222:225], v[182:185], v[168:171]
	v_mfma_f32_16x16x32_bf16 v[12:15], v[210:213], v[198:201], v[12:15]
	v_mfma_f32_16x16x32_bf16 v[8:11], v[222:225], v[198:201], v[8:11]
	v_mfma_f32_16x16x32_bf16 v[88:91], v[214:217], v[178:181], v[28:31]
	v_mfma_f32_16x16x32_bf16 v[60:63], v[242:245], v[186:189], v[24:27]
	v_mfma_f32_16x16x32_bf16 v[24:27], v[214:217], v[202:205], v[12:15]
	v_mfma_f32_16x16x32_bf16 v[28:31], v[242:245], v[202:205], v[8:11]
	v_mfma_f32_16x16x32_bf16 v[8:11], v[210:213], v[218:221], v[172:175]
	v_mfma_f32_16x16x32_bf16 v[12:15], v[222:225], v[218:221], v[146:149]
	v_mfma_f32_16x16x32_bf16 v[8:11], v[214:217], v[142:145], v[8:11]
	v_mfma_f32_16x16x32_bf16 v[12:15], v[242:245], v[142:145], v[12:15]
	s_setprio 0
	s_cmpk_lt_u32 s9, 0x100
	s_barrier
	s_cbranch_scc0 .LBB0_66
	s_barrier

.LBB0_93:
	s_waitcnt vmcnt(2)
	s_add_u32 s28, s28, 0x80
	s_addc_u32 s29, s29, 0
	s_and_b64 vcc, exec, s[42:43]
	v_mov_b32_e32 v8, v128
	s_barrier
	s_cbranch_vccz .LBB0_870
	s_and_b64 vcc, exec, s[42:43]
	v_mov_b64_e32 v[0:1], v[176:177]
	s_cbranch_vccz .LBB0_871

.LBB0_105:
	ds_read_b128 v[148:151], v145 offset:0
	ds_read_b128 v[152:155], v145 offset:1024
	ds_read_b128 v[160:163], v145 offset:2048
	ds_read_b128 v[164:167], v145 offset:3072
	s_add_u32 s35, s1, s40
	s_addc_u32 s43, s26, s41
	s_add_u32 s42, s35, 0x80
	v_add_u32_e32 v158, 0xc000, v134
	s_addc_u32 s43, s43, 0
	v_readfirstlane_b32 s35, v158
	v_add_u32_e32 v159, 0xe000, v134
	v_lshl_add_u64 v[146:147], s[42:43], 0, v[128:129]
	s_mov_b32 m0, s35
	v_readfirstlane_b32 s35, v159
	ds_read_b128 v[168:171], v144 offset:0
	ds_read_b128 v[172:175], v144 offset:1024
	ds_read_b128 v[178:181], v144 offset:2048
	ds_read_b128 v[182:185], v144 offset:3072
	ds_read_b128 v[186:189], v144 offset:4096
	ds_read_b128 v[190:193], v144 offset:5120
	ds_read_b128 v[194:197], v144 offset:6144
	ds_read_b128 v[198:201], v144 offset:7168
	global_load_lds_dwordx4 v[146:147], off
	v_lshl_add_u64 v[146:147], s[42:43], 0, v[130:131]
	s_mov_b32 m0, s35
	s_nop 0
	global_load_lds_dwordx4 v[146:147], off
	ds_read_b128 v[202:205], v143 offset:0
	ds_read_b128 v[206:209], v143 offset:1024
	ds_read_b128 v[210:213], v143 offset:2048
	ds_read_b128 v[214:217], v143 offset:3072
	s_waitcnt vmcnt(8)
	s_waitcnt lgkmcnt(0)
	s_barrier
	s_waitcnt lgkmcnt(0)
	s_waitcnt lgkmcnt(0)
	s_setprio 1
	v_mfma_f32_16x16x32_bf16 v[124:127], v[148:151], v[168:171], v[124:127]
	v_mfma_f32_16x16x32_bf16 v[120:123], v[160:163], v[168:171], v[120:123]
	v_mfma_f32_16x16x32_bf16 v[116:119], v[148:151], v[178:181], v[116:119]
	v_mfma_f32_16x16x32_bf16 v[112:115], v[160:163], v[178:181], v[112:115]
	v_mfma_f32_16x16x32_bf16 v[108:111], v[148:151], v[186:189], v[108:111]
	v_mfma_f32_16x16x32_bf16 v[104:107], v[160:163], v[186:189], v[104:107]
	v_mfma_f32_16x16x32_bf16 v[100:103], v[148:151], v[194:197], v[100:103]
	v_mfma_f32_16x16x32_bf16 v[96:99], v[160:163], v[194:197], v[96:99]
	v_mfma_f32_16x16x32_bf16 v[124:127], v[152:155], v[172:175], v[124:127]
	v_mfma_f32_16x16x32_bf16 v[120:123], v[164:167], v[172:175], v[120:123]
	v_mfma_f32_16x16x32_bf16 v[116:119], v[152:155], v[182:185], v[116:119]
	v_mfma_f32_16x16x32_bf16 v[112:115], v[164:167], v[182:185], v[112:115]
	v_mfma_f32_16x16x32_bf16 v[108:111], v[152:155], v[190:193], v[108:111]
	v_mfma_f32_16x16x32_bf16 v[104:107], v[164:167], v[190:193], v[104:107]
	v_mfma_f32_16x16x32_bf16 v[100:103], v[152:155], v[198:201], v[100:103]
	v_mfma_f32_16x16x32_bf16 v[96:99], v[164:167], v[198:201], v[96:99]
	s_setprio 0
	s_waitcnt lgkmcnt(0)
	s_setprio 1
	v_mfma_f32_16x16x32_bf16 v[92:95], v[202:205], v[168:171], v[92:95]
	v_mfma_f32_16x16x32_bf16 v[88:91], v[210:213], v[168:171], v[88:91]
	v_mfma_f32_16x16x32_bf16 v[84:87], v[202:205], v[178:181], v[84:87]
	v_mfma_f32_16x16x32_bf16 v[80:83], v[210:213], v[178:181], v[80:83]
	v_mfma_f32_16x16x32_bf16 v[76:79], v[202:205], v[186:189], v[76:79]
	v_mfma_f32_16x16x32_bf16 v[72:75], v[210:213], v[186:189], v[72:75]
	v_mfma_f32_16x16x32_bf16 v[68:71], v[202:205], v[194:197], v[68:71]
	v_mfma_f32_16x16x32_bf16 v[64:67], v[210:213], v[194:197], v[64:67]
	v_mfma_f32_16x16x32_bf16 v[92:95], v[206:209], v[172:175], v[92:95]
	v_mfma_f32_16x16x32_bf16 v[88:91], v[214:217], v[172:175], v[88:91]
	v_mfma_f32_16x16x32_bf16 v[84:87], v[206:209], v[182:185], v[84:87]
	v_mfma_f32_16x16x32_bf16 v[80:83], v[214:217], v[182:185], v[80:83]
	v_mfma_f32_16x16x32_bf16 v[76:79], v[206:209], v[190:193], v[76:79]
	v_mfma_f32_16x16x32_bf16 v[72:75], v[214:217], v[190:193], v[72:75]
	v_mfma_f32_16x16x32_bf16 v[68:71], v[206:209], v[198:201], v[68:71]
	v_mfma_f32_16x16x32_bf16 v[64:67], v[214:217], v[198:201], v[64:67]
	s_setprio 0
	s_barrier
	s_add_u32 s35, s2, s40
	s_addc_u32 s45, s3, s41
	s_add_u32 s42, s35, 0x100
	v_add_u32_e32 v146, 0x10000, v134
	s_addc_u32 s43, s45, 0
	v_readfirstlane_b32 s51, v146
	v_lshl_add_u64 v[156:157], s[42:43], 0, v[176:177]
	s_mov_b32 m0, s51
	v_add_u32_e32 v147, 0x12000, v134
	global_load_lds_dwordx4 v[156:157], off
	v_lshl_add_u64 v[156:157], s[42:43], 0, v[132:133]
	v_readfirstlane_b32 s42, v147
	s_mov_b32 m0, s42
	s_nop 0
	global_load_lds_dwordx4 v[156:157], off
	s_add_u32 s51, s20, s40
	s_addc_u32 s54, s21, s41
	s_add_u32 s42, s51, 0x100
	s_addc_u32 s43, s54, 0
	v_readfirstlane_b32 s88, v134
	v_lshl_add_u64 v[156:157], s[42:43], 0, v[128:129]
	s_mov_b32 m0, s88
	ds_read_b128 v[168:171], v142 offset:0
	ds_read_b128 v[172:175], v142 offset:1024
	ds_read_b128 v[178:181], v142 offset:2048
	ds_read_b128 v[182:185], v142 offset:3072
	ds_read_b128 v[186:189], v142 offset:4096
	ds_read_b128 v[190:193], v142 offset:5120
	ds_read_b128 v[194:197], v142 offset:6144
	ds_read_b128 v[198:201], v142 offset:7168
	global_load_lds_dwordx4 v[156:157], off
	v_lshl_add_u64 v[156:157], s[42:43], 0, v[130:131]
	v_readfirstlane_b32 s42, v135
	s_mov_b32 m0, s42
	s_nop 0
	global_load_lds_dwordx4 v[156:157], off
	s_add_u32 s88, s27, s40
	s_addc_u32 s89, s28, s41
	s_add_u32 s42, s88, 0x100
	v_add_u32_e32 v226, 0x14000, v134
	s_addc_u32 s43, s89, 0
	v_readfirstlane_b32 s96, v226
	v_lshl_add_u64 v[228:229], s[42:43], 0, v[176:177]
	s_mov_b32 m0, s96
	v_add_u32_e32 v227, 0x16000, v134
	global_load_lds_dwordx4 v[228:229], off
	v_lshl_add_u64 v[228:229], s[42:43], 0, v[132:133]
	v_readfirstlane_b32 s42, v227
	s_mov_b32 m0, s42
	s_nop 0
	global_load_lds_dwordx4 v[228:229], off
	s_waitcnt vmcnt(8)
	s_waitcnt lgkmcnt(0)
	s_barrier
	s_waitcnt lgkmcnt(0)
	s_setprio 1
	v_mfma_f32_16x16x32_bf16 v[60:63], v[148:151], v[168:171], v[60:63]
	v_mfma_f32_16x16x32_bf16 v[56:59], v[160:163], v[168:171], v[56:59]
	v_mfma_f32_16x16x32_bf16 v[52:55], v[148:151], v[178:181], v[52:55]
	v_mfma_f32_16x16x32_bf16 v[48:51], v[160:163], v[178:181], v[48:51]
	v_mfma_f32_16x16x32_bf16 v[44:47], v[148:151], v[186:189], v[44:47]
	v_mfma_f32_16x16x32_bf16 v[40:43], v[160:163], v[186:189], v[40:43]
	v_mfma_f32_16x16x32_bf16 v[36:39], v[148:151], v[194:197], v[36:39]
	v_mfma_f32_16x16x32_bf16 v[32:35], v[160:163], v[194:197], v[32:35]
	v_mfma_f32_16x16x32_bf16 v[60:63], v[152:155], v[172:175], v[60:63]
	v_mfma_f32_16x16x32_bf16 v[56:59], v[164:167], v[172:175], v[56:59]
	v_mfma_f32_16x16x32_bf16 v[52:55], v[152:155], v[182:185], v[52:55]
	v_mfma_f32_16x16x32_bf16 v[48:51], v[164:167], v[182:185], v[48:51]
	v_mfma_f32_16x16x32_bf16 v[44:47], v[152:155], v[190:193], v[44:47]
	v_mfma_f32_16x16x32_bf16 v[40:43], v[164:167], v[190:193], v[40:43]
	v_mfma_f32_16x16x32_bf16 v[36:39], v[152:155], v[198:201], v[36:39]
	v_mfma_f32_16x16x32_bf16 v[32:35], v[164:167], v[198:201], v[32:35]
	s_setprio 0
	s_setprio 1
	v_mfma_f32_16x16x32_bf16 v[28:31], v[202:205], v[168:171], v[28:31]
	v_mfma_f32_16x16x32_bf16 v[24:27], v[210:213], v[168:171], v[24:27]
	v_mfma_f32_16x16x32_bf16 v[20:23], v[202:205], v[178:181], v[20:23]
	v_mfma_f32_16x16x32_bf16 v[16:19], v[210:213], v[178:181], v[16:19]
	v_mfma_f32_16x16x32_bf16 v[12:15], v[202:205], v[186:189], v[12:15]
	v_mfma_f32_16x16x32_bf16 v[8:11], v[210:213], v[186:189], v[8:11]
	v_mfma_f32_16x16x32_bf16 v[4:7], v[202:205], v[194:197], v[4:7]
	v_mfma_f32_16x16x32_bf16 v[0:3], v[210:213], v[194:197], v[0:3]
	v_mfma_f32_16x16x32_bf16 v[28:31], v[206:209], v[172:175], v[28:31]
	v_mfma_f32_16x16x32_bf16 v[24:27], v[214:217], v[172:175], v[24:27]
	v_mfma_f32_16x16x32_bf16 v[20:23], v[206:209], v[182:185], v[20:23]
	v_mfma_f32_16x16x32_bf16 v[16:19], v[214:217], v[182:185], v[16:19]
	v_mfma_f32_16x16x32_bf16 v[12:15], v[206:209], v[190:193], v[12:15]
	v_mfma_f32_16x16x32_bf16 v[8:11], v[214:217], v[190:193], v[8:11]
	v_mfma_f32_16x16x32_bf16 v[4:7], v[206:209], v[198:201], v[4:7]
	v_mfma_f32_16x16x32_bf16 v[0:3], v[214:217], v[198:201], v[0:3]
	s_setprio 0
	s_barrier
	ds_read_b128 v[160:163], v141 offset:0
	ds_read_b128 v[164:167], v141 offset:1024
	ds_read_b128 v[168:171], v141 offset:2048
	ds_read_b128 v[172:175], v141 offset:3072
	s_add_u32 s42, s29, s40
	v_add_u32_e32 v150, 0x4000, v134
	s_addc_u32 s43, s30, s41
	v_readfirstlane_b32 s96, v150
	v_lshl_add_u64 v[152:153], s[42:43], 0, v[128:129]
	s_mov_b32 m0, s96
	v_add_u32_e32 v151, 0x6000, v134
	ds_read_b128 v[154:157], v140 offset:0
	ds_read_b128 v[178:181], v140 offset:1024
	ds_read_b128 v[182:185], v140 offset:2048
	ds_read_b128 v[186:189], v140 offset:3072
	ds_read_b128 v[190:193], v140 offset:4096
	ds_read_b128 v[194:197], v140 offset:5120
	ds_read_b128 v[198:201], v140 offset:6144
	ds_read_b128 v[202:205], v140 offset:7168
	global_load_lds_dwordx4 v[152:153], off
	v_lshl_add_u64 v[152:153], s[42:43], 0, v[130:131]
	v_readfirstlane_b32 s42, v151
	s_mov_b32 m0, s42
	s_nop 0
	global_load_lds_dwordx4 v[152:153], off
	ds_read_b128 v[206:209], v139 offset:0
	ds_read_b128 v[210:213], v139 offset:1024
	ds_read_b128 v[214:217], v139 offset:2048
	ds_read_b128 v[218:221], v139 offset:3072
	s_waitcnt vmcnt(8)
	s_waitcnt lgkmcnt(0)
	s_barrier
	s_waitcnt lgkmcnt(0)
	s_waitcnt lgkmcnt(0)
	s_setprio 1
	v_mfma_f32_16x16x32_bf16 v[124:127], v[160:163], v[154:157], v[124:127]
	v_mfma_f32_16x16x32_bf16 v[120:123], v[168:171], v[154:157], v[120:123]
	v_mfma_f32_16x16x32_bf16 v[116:119], v[160:163], v[182:185], v[116:119]
	v_mfma_f32_16x16x32_bf16 v[112:115], v[168:171], v[182:185], v[112:115]
	v_mfma_f32_16x16x32_bf16 v[108:111], v[160:163], v[190:193], v[108:111]
	v_mfma_f32_16x16x32_bf16 v[104:107], v[168:171], v[190:193], v[104:107]
	v_mfma_f32_16x16x32_bf16 v[100:103], v[160:163], v[198:201], v[100:103]
	v_mfma_f32_16x16x32_bf16 v[96:99], v[168:171], v[198:201], v[96:99]
	v_mfma_f32_16x16x32_bf16 v[124:127], v[164:167], v[178:181], v[124:127]
	v_mfma_f32_16x16x32_bf16 v[120:123], v[172:175], v[178:181], v[120:123]
	v_mfma_f32_16x16x32_bf16 v[116:119], v[164:167], v[186:189], v[116:119]
	v_mfma_f32_16x16x32_bf16 v[112:115], v[172:175], v[186:189], v[112:115]
	v_mfma_f32_16x16x32_bf16 v[108:111], v[164:167], v[194:197], v[108:111]
	v_mfma_f32_16x16x32_bf16 v[104:107], v[172:175], v[194:197], v[104:107]
	v_mfma_f32_16x16x32_bf16 v[100:103], v[164:167], v[202:205], v[100:103]
	v_mfma_f32_16x16x32_bf16 v[96:99], v[172:175], v[202:205], v[96:99]
	s_setprio 0
	s_waitcnt lgkmcnt(0)
	s_setprio 1
	v_mfma_f32_16x16x32_bf16 v[92:95], v[206:209], v[154:157], v[92:95]
	v_mfma_f32_16x16x32_bf16 v[88:91], v[214:217], v[154:157], v[88:91]
	v_mfma_f32_16x16x32_bf16 v[84:87], v[206:209], v[182:185], v[84:87]
	v_mfma_f32_16x16x32_bf16 v[80:83], v[214:217], v[182:185], v[80:83]
	v_mfma_f32_16x16x32_bf16 v[76:79], v[206:209], v[190:193], v[76:79]
	v_mfma_f32_16x16x32_bf16 v[72:75], v[214:217], v[190:193], v[72:75]
	v_mfma_f32_16x16x32_bf16 v[68:71], v[206:209], v[198:201], v[68:71]
	v_mfma_f32_16x16x32_bf16 v[64:67], v[214:217], v[198:201], v[64:67]
	v_mfma_f32_16x16x32_bf16 v[92:95], v[210:213], v[178:181], v[92:95]
	v_mfma_f32_16x16x32_bf16 v[88:91], v[218:221], v[178:181], v[88:91]
	v_mfma_f32_16x16x32_bf16 v[84:87], v[210:213], v[186:189], v[84:87]
	v_mfma_f32_16x16x32_bf16 v[80:83], v[218:221], v[186:189], v[80:83]
	v_mfma_f32_16x16x32_bf16 v[76:79], v[210:213], v[194:197], v[76:79]
	v_mfma_f32_16x16x32_bf16 v[72:75], v[218:221], v[194:197], v[72:75]
	v_mfma_f32_16x16x32_bf16 v[68:71], v[210:213], v[202:205], v[68:71]
	v_mfma_f32_16x16x32_bf16 v[64:67], v[218:221], v[202:205], v[64:67]
	s_setprio 0
	s_barrier
	s_add_u32 s42, s35, 0x180
	v_add_u32_e32 v152, 0x18000, v134
	s_addc_u32 s43, s45, 0
	v_readfirstlane_b32 s35, v152
	v_add_u32_e32 v153, 0x1a000, v134
	v_lshl_add_u64 v[222:223], s[42:43], 0, v[176:177]
	s_mov_b32 m0, s35
	v_readfirstlane_b32 s35, v153
	global_load_lds_dwordx4 v[222:223], off
	v_lshl_add_u64 v[222:223], s[42:43], 0, v[132:133]
	s_mov_b32 m0, s35
	s_nop 0
	global_load_lds_dwordx4 v[222:223], off
	s_add_u32 s42, s51, 0x180
	v_add_u32_e32 v154, 0x8000, v134
	s_addc_u32 s43, s54, 0
	v_readfirstlane_b32 s35, v154
	v_add_u32_e32 v155, 0xa000, v134
	v_lshl_add_u64 v[156:157], s[42:43], 0, v[128:129]
	s_mov_b32 m0, s35
	v_readfirstlane_b32 s35, v155
	ds_read_b128 v[178:181], v138 offset:0
	ds_read_b128 v[182:185], v138 offset:1024
	ds_read_b128 v[186:189], v138 offset:2048
	ds_read_b128 v[190:193], v138 offset:3072
	ds_read_b128 v[194:197], v138 offset:4096
	ds_read_b128 v[198:201], v138 offset:5120
	ds_read_b128 v[202:205], v138 offset:6144
	ds_read_b128 v[222:225], v138 offset:7168
	global_load_lds_dwordx4 v[156:157], off
	v_lshl_add_u64 v[156:157], s[42:43], 0, v[130:131]
	s_mov_b32 m0, s35
	s_nop 0
	global_load_lds_dwordx4 v[156:157], off
	s_add_u32 s42, s88, 0x180
	v_add_u32_e32 v156, 0x1c000, v134
	s_addc_u32 s43, s89, 0
	v_readfirstlane_b32 s35, v156
	v_add_u32_e32 v157, 0x1e000, v134
	v_lshl_add_u64 v[226:227], s[42:43], 0, v[176:177]
	s_mov_b32 m0, s35
	v_readfirstlane_b32 s35, v157
	global_load_lds_dwordx4 v[226:227], off
	v_lshl_add_u64 v[226:227], s[42:43], 0, v[132:133]
	s_mov_b32 m0, s35
	s_nop 0
	global_load_lds_dwordx4 v[226:227], off
	s_waitcnt vmcnt(8)
	s_waitcnt lgkmcnt(0)
	s_barrier
	s_waitcnt lgkmcnt(0)
	s_setprio 1
	v_mfma_f32_16x16x32_bf16 v[60:63], v[160:163], v[178:181], v[60:63]
	v_mfma_f32_16x16x32_bf16 v[56:59], v[168:171], v[178:181], v[56:59]
	v_mfma_f32_16x16x32_bf16 v[52:55], v[160:163], v[186:189], v[52:55]
	v_mfma_f32_16x16x32_bf16 v[48:51], v[168:171], v[186:189], v[48:51]
	v_mfma_f32_16x16x32_bf16 v[44:47], v[160:163], v[194:197], v[44:47]
	v_mfma_f32_16x16x32_bf16 v[40:43], v[168:171], v[194:197], v[40:43]
	v_mfma_f32_16x16x32_bf16 v[36:39], v[160:163], v[202:205], v[36:39]
	v_mfma_f32_16x16x32_bf16 v[32:35], v[168:171], v[202:205], v[32:35]
	v_mfma_f32_16x16x32_bf16 v[60:63], v[164:167], v[182:185], v[60:63]
	v_mfma_f32_16x16x32_bf16 v[56:59], v[172:175], v[182:185], v[56:59]
	v_mfma_f32_16x16x32_bf16 v[52:55], v[164:167], v[190:193], v[52:55]
	v_mfma_f32_16x16x32_bf16 v[48:51], v[172:175], v[190:193], v[48:51]
	v_mfma_f32_16x16x32_bf16 v[44:47], v[164:167], v[198:201], v[44:47]
	v_mfma_f32_16x16x32_bf16 v[40:43], v[172:175], v[198:201], v[40:43]
	v_mfma_f32_16x16x32_bf16 v[36:39], v[164:167], v[222:225], v[36:39]
	v_mfma_f32_16x16x32_bf16 v[32:35], v[172:175], v[222:225], v[32:35]
	s_setprio 0
	s_setprio 1
	v_mfma_f32_16x16x32_bf16 v[28:31], v[206:209], v[178:181], v[28:31]
	v_mfma_f32_16x16x32_bf16 v[24:27], v[214:217], v[178:181], v[24:27]
	v_mfma_f32_16x16x32_bf16 v[20:23], v[206:209], v[186:189], v[20:23]
	v_mfma_f32_16x16x32_bf16 v[16:19], v[214:217], v[186:189], v[16:19]
	v_mfma_f32_16x16x32_bf16 v[12:15], v[206:209], v[194:197], v[12:15]
	v_mfma_f32_16x16x32_bf16 v[8:11], v[214:217], v[194:197], v[8:11]
	v_mfma_f32_16x16x32_bf16 v[4:7], v[206:209], v[202:205], v[4:7]
	v_mfma_f32_16x16x32_bf16 v[0:3], v[214:217], v[202:205], v[0:3]
	v_mfma_f32_16x16x32_bf16 v[28:31], v[210:213], v[182:185], v[28:31]
	v_mfma_f32_16x16x32_bf16 v[24:27], v[218:221], v[182:185], v[24:27]
	v_mfma_f32_16x16x32_bf16 v[20:23], v[210:213], v[190:193], v[20:23]
	v_mfma_f32_16x16x32_bf16 v[16:19], v[218:221], v[190:193], v[16:19]
	v_mfma_f32_16x16x32_bf16 v[12:15], v[210:213], v[198:201], v[12:15]
	v_mfma_f32_16x16x32_bf16 v[8:11], v[218:221], v[198:201], v[8:11]
	v_mfma_f32_16x16x32_bf16 v[4:7], v[210:213], v[222:225], v[4:7]
	v_mfma_f32_16x16x32_bf16 v[0:3], v[218:221], v[222:225], v[0:3]
	s_setprio 0
	s_add_i32 s31, s31, 2
	s_add_u32 s40, s40, 0x100
	s_addc_u32 s41, s41, 0
	s_cmp_gt_u32 s31, 11
	s_barrier
	s_cbranch_scc0 .LBB0_105
	v_add_u32_e32 v158, 0xc000, v134
	v_add_u32_e32 v159, 0xe000, v134
	v_add_u32_e32 v146, 0x10000, v134
	v_add_u32_e32 v147, 0x12000, v134
	v_add_u32_e32 v148, 0x14000, v134
	v_add_u32_e32 v149, 0x16000, v134
	v_add_u32_e32 v150, 0x4000, v134
	v_add_u32_e32 v151, 0x6000, v134
	v_add_u32_e32 v152, 0x18000, v134
	v_add_u32_e32 v153, 0x1a000, v134
	v_add_u32_e32 v154, 0x8000, v134
	v_add_u32_e32 v155, 0xa000, v134
	v_add_u32_e32 v156, 0x1c000, v134
	v_add_u32_e32 v157, 0x1e000, v134
	s_add_u32 s2, s1, 0x780
	s_addc_u32 s3, s26, 0
	v_readfirstlane_b32 s1, v158
	v_lshl_add_u64 v[132:133], s[2:3], 0, v[128:129]
	s_mov_b32 m0, s1
	v_readfirstlane_b32 s1, v159
	ds_read_b128 v[160:163], v145 offset:0
	ds_read_b128 v[164:167], v145 offset:1024
	ds_read_b128 v[168:171], v145 offset:2048
	ds_read_b128 v[172:175], v145 offset:3072
	ds_read_b128 v[178:181], v144 offset:0
	ds_read_b128 v[182:185], v144 offset:1024
	ds_read_b128 v[186:189], v144 offset:2048
	ds_read_b128 v[190:193], v144 offset:3072
	ds_read_b128 v[194:197], v144 offset:4096
	ds_read_b128 v[198:201], v144 offset:5120
	ds_read_b128 v[202:205], v144 offset:6144
	ds_read_b128 v[206:209], v144 offset:7168
	global_load_lds_dwordx4 v[132:133], off
	v_lshl_add_u64 v[132:133], s[2:3], 0, v[130:131]
	s_mov_b32 m0, s1
	s_nop 0
	global_load_lds_dwordx4 v[132:133], off
	s_waitcnt vmcnt(10)
	s_barrier
	s_waitcnt lgkmcnt(0)
	s_waitcnt lgkmcnt(0)
	s_setprio 1
	v_mfma_f32_16x16x32_bf16 v[124:127], v[160:163], v[178:181], v[124:127]
	v_mfma_f32_16x16x32_bf16 v[120:123], v[168:171], v[178:181], v[120:123]
	v_mfma_f32_16x16x32_bf16 v[116:119], v[160:163], v[186:189], v[116:119]
	v_mfma_f32_16x16x32_bf16 v[112:115], v[168:171], v[186:189], v[112:115]
	v_mfma_f32_16x16x32_bf16 v[100:103], v[160:163], v[202:205], v[100:103]
	v_mfma_f32_16x16x32_bf16 v[96:99], v[168:171], v[202:205], v[96:99]
	v_mfma_f32_16x16x32_bf16 v[124:127], v[164:167], v[182:185], v[124:127]
	v_mfma_f32_16x16x32_bf16 v[120:123], v[172:175], v[182:185], v[120:123]
	v_mfma_f32_16x16x32_bf16 v[116:119], v[164:167], v[190:193], v[116:119]
	v_mfma_f32_16x16x32_bf16 v[112:115], v[172:175], v[190:193], v[112:115]
	v_mfma_f32_16x16x32_bf16 v[108:111], v[160:163], v[194:197], v[108:111]
	v_mfma_f32_16x16x32_bf16 v[104:107], v[168:171], v[194:197], v[104:107]
	v_mfma_f32_16x16x32_bf16 v[100:103], v[164:167], v[206:209], v[100:103]
	v_mfma_f32_16x16x32_bf16 v[96:99], v[172:175], v[206:209], v[96:99]
	v_mfma_f32_16x16x32_bf16 v[210:213], v[164:167], v[198:201], v[108:111]
	v_mfma_f32_16x16x32_bf16 v[214:217], v[172:175], v[198:201], v[104:107]
	s_setprio 0
	s_barrier
	ds_read_b128 v[104:107], v143 offset:0
	ds_read_b128 v[108:111], v143 offset:1024
	ds_read_b128 v[218:221], v143 offset:2048
	ds_read_b128 v[222:225], v143 offset:3072
	s_waitcnt vmcnt(8)
	s_barrier
	s_waitcnt lgkmcnt(0)
	s_setprio 1
	v_mfma_f32_16x16x32_bf16 v[92:95], v[104:107], v[178:181], v[92:95]
	v_mfma_f32_16x16x32_bf16 v[88:91], v[218:221], v[178:181], v[88:91]
	v_mfma_f32_16x16x32_bf16 v[76:79], v[104:107], v[194:197], v[76:79]
	v_mfma_f32_16x16x32_bf16 v[72:75], v[218:221], v[194:197], v[72:75]
	v_mfma_f32_16x16x32_bf16 v[68:71], v[104:107], v[202:205], v[68:71]
	v_mfma_f32_16x16x32_bf16 v[92:95], v[108:111], v[182:185], v[92:95]
	v_mfma_f32_16x16x32_bf16 v[88:91], v[222:225], v[182:185], v[88:91]
	v_mfma_f32_16x16x32_bf16 v[84:87], v[104:107], v[186:189], v[84:87]
	v_mfma_f32_16x16x32_bf16 v[80:83], v[218:221], v[186:189], v[80:83]
	v_mfma_f32_16x16x32_bf16 v[76:79], v[108:111], v[198:201], v[76:79]
	v_mfma_f32_16x16x32_bf16 v[72:75], v[222:225], v[198:201], v[72:75]
	v_mfma_f32_16x16x32_bf16 v[68:71], v[108:111], v[206:209], v[68:71]
	v_mfma_f32_16x16x32_bf16 v[64:67], v[218:221], v[202:205], v[64:67]
	v_mfma_f32_16x16x32_bf16 v[178:181], v[108:111], v[190:193], v[84:87]
	v_mfma_f32_16x16x32_bf16 v[182:185], v[222:225], v[190:193], v[80:83]
	v_mfma_f32_16x16x32_bf16 v[186:189], v[222:225], v[206:209], v[64:67]
	s_setprio 0
	s_barrier
	ds_read_b128 v[64:67], v142 offset:0
	ds_read_b128 v[80:83], v142 offset:1024
	ds_read_b128 v[84:87], v142 offset:2048
	ds_read_b128 v[190:193], v142 offset:3072
	ds_read_b128 v[194:197], v142 offset:4096
	ds_read_b128 v[198:201], v142 offset:5120
	ds_read_b128 v[202:205], v142 offset:6144
	ds_read_b128 v[142:145], v142 offset:7168
	s_waitcnt vmcnt(4)
	s_barrier
	s_waitcnt lgkmcnt(0)
	s_setprio 1
	s_nop 0
	v_mfma_f32_16x16x32_bf16 v[60:63], v[160:163], v[64:67], v[60:63]
	v_mfma_f32_16x16x32_bf16 v[56:59], v[168:171], v[64:67], v[56:59]
	v_mfma_f32_16x16x32_bf16 v[60:63], v[164:167], v[80:83], v[60:63]
	v_mfma_f32_16x16x32_bf16 v[56:59], v[172:175], v[80:83], v[56:59]
	v_mfma_f32_16x16x32_bf16 v[52:55], v[160:163], v[84:87], v[52:55]
	v_mfma_f32_16x16x32_bf16 v[48:51], v[168:171], v[84:87], v[48:51]
	v_mfma_f32_16x16x32_bf16 v[44:47], v[160:163], v[194:197], v[44:47]
	v_mfma_f32_16x16x32_bf16 v[40:43], v[168:171], v[194:197], v[40:43]
	v_mfma_f32_16x16x32_bf16 v[36:39], v[160:163], v[202:205], v[36:39]
	v_mfma_f32_16x16x32_bf16 v[32:35], v[168:171], v[202:205], v[32:35]
	v_mfma_f32_16x16x32_bf16 v[206:209], v[164:167], v[190:193], v[52:55]
	v_mfma_f32_16x16x32_bf16 v[226:229], v[172:175], v[190:193], v[48:51]
	v_mfma_f32_16x16x32_bf16 v[232:235], v[164:167], v[198:201], v[44:47]
	v_mfma_f32_16x16x32_bf16 v[238:241], v[172:175], v[198:201], v[40:43]
	v_mfma_f32_16x16x32_bf16 v[158:161], v[164:167], v[142:145], v[36:39]
	v_mfma_f32_16x16x32_bf16 v[162:165], v[172:175], v[142:145], v[32:35]
	s_setprio 0
	s_setprio 1
	v_mfma_f32_16x16x32_bf16 v[28:31], v[104:107], v[64:67], v[28:31]
	v_mfma_f32_16x16x32_bf16 v[24:27], v[218:221], v[64:67], v[24:27]
	v_mfma_f32_16x16x32_bf16 v[12:15], v[104:107], v[194:197], v[12:15]
	v_mfma_f32_16x16x32_bf16 v[8:11], v[218:221], v[194:197], v[8:11]
	v_mfma_f32_16x16x32_bf16 v[28:31], v[108:111], v[80:83], v[28:31]
	v_mfma_f32_16x16x32_bf16 v[24:27], v[222:225], v[80:83], v[24:27]
	v_mfma_f32_16x16x32_bf16 v[20:23], v[104:107], v[84:87], v[20:23]
	v_mfma_f32_16x16x32_bf16 v[16:19], v[218:221], v[84:87], v[16:19]
	v_mfma_f32_16x16x32_bf16 v[12:15], v[108:111], v[198:201], v[12:15]
	v_mfma_f32_16x16x32_bf16 v[8:11], v[222:225], v[198:201], v[8:11]
	v_mfma_f32_16x16x32_bf16 v[4:7], v[104:107], v[202:205], v[4:7]
	v_mfma_f32_16x16x32_bf16 v[0:3], v[218:221], v[202:205], v[0:3]
	v_mfma_f32_16x16x32_bf16 v[166:169], v[108:111], v[190:193], v[20:23]
	v_mfma_f32_16x16x32_bf16 v[170:173], v[222:225], v[190:193], v[16:19]
	v_mfma_f32_16x16x32_bf16 v[190:193], v[108:111], v[142:145], v[4:7]
	v_mfma_f32_16x16x32_bf16 v[142:145], v[222:225], v[142:145], v[0:3]
	s_setprio 0
	s_barrier
	ds_read_b128 v[0:3], v141 offset:0
	ds_read_b128 v[4:7], v141 offset:1024
	ds_read_b128 v[194:197], v141 offset:2048
	ds_read_b128 v[198:201], v141 offset:3072
	ds_read_b128 v[16:19], v140 offset:0
	ds_read_b128 v[20:23], v140 offset:1024
	ds_read_b128 v[40:43], v140 offset:2048
	ds_read_b128 v[44:47], v140 offset:3072
	ds_read_b128 v[64:67], v140 offset:4096
	ds_read_b128 v[202:205], v140 offset:5120
	ds_read_b128 v[218:221], v140 offset:6144
	ds_read_b128 v[222:225], v140 offset:7168
	s_waitcnt vmcnt(2)
	s_barrier
	s_waitcnt lgkmcnt(0)
	s_waitcnt lgkmcnt(0)
	s_setprio 1
	v_mfma_f32_16x16x32_bf16 v[32:35], v[0:3], v[16:19], v[124:127]
	v_mfma_f32_16x16x32_bf16 v[104:107], v[4:7], v[20:23], v[32:35]
	v_mfma_f32_16x16x32_bf16 v[32:35], v[194:197], v[16:19], v[120:123]
	v_mfma_f32_16x16x32_bf16 v[108:111], v[198:201], v[20:23], v[32:35]
	v_mfma_f32_16x16x32_bf16 v[32:35], v[0:3], v[40:43], v[116:119]
	v_mfma_f32_16x16x32_bf16 v[80:83], v[4:7], v[44:47], v[32:35]
	v_mfma_f32_16x16x32_bf16 v[32:35], v[194:197], v[40:43], v[112:115]
	v_mfma_f32_16x16x32_bf16 v[84:87], v[198:201], v[44:47], v[32:35]
	v_mfma_f32_16x16x32_bf16 v[32:35], v[0:3], v[64:67], v[210:213]
	v_mfma_f32_16x16x32_bf16 v[48:51], v[4:7], v[202:205], v[32:35]
	v_mfma_f32_16x16x32_bf16 v[32:35], v[194:197], v[64:67], v[214:217]
	v_mfma_f32_16x16x32_bf16 v[52:55], v[198:201], v[202:205], v[32:35]
	v_mfma_f32_16x16x32_bf16 v[32:35], v[0:3], v[218:221], v[100:103]
	v_mfma_f32_16x16x32_bf16 v[36:39], v[194:197], v[218:221], v[96:99]
	v_mfma_f32_16x16x32_bf16 v[32:35], v[4:7], v[222:225], v[32:35]
	v_mfma_f32_16x16x32_bf16 v[36:39], v[198:201], v[222:225], v[36:39]
	s_setprio 0
	s_barrier
	ds_read_b128 v[210:213], v139 offset:0
	ds_read_b128 v[214:217], v139 offset:1024
	ds_read_b128 v[242:245], v139 offset:2048
	ds_read_b128 v[246:249], v139 offset:3072
	s_waitcnt vmcnt(0)
	s_barrier
	s_waitcnt lgkmcnt(0)
	s_setprio 1
	v_mfma_f32_16x16x32_bf16 v[92:95], v[210:213], v[16:19], v[92:95]
	v_mfma_f32_16x16x32_bf16 v[16:19], v[242:245], v[16:19], v[88:91]
	v_mfma_f32_16x16x32_bf16 v[124:127], v[246:249], v[20:23], v[16:19]
	v_mfma_f32_16x16x32_bf16 v[16:19], v[210:213], v[40:43], v[178:181]
	v_mfma_f32_16x16x32_bf16 v[112:115], v[214:217], v[44:47], v[16:19]
	v_mfma_f32_16x16x32_bf16 v[16:19], v[242:245], v[40:43], v[182:185]
	v_mfma_f32_16x16x32_bf16 v[116:119], v[246:249], v[44:47], v[16:19]
	v_mfma_f32_16x16x32_bf16 v[16:19], v[210:213], v[64:67], v[76:79]
	v_mfma_f32_16x16x32_bf16 v[96:99], v[214:217], v[202:205], v[16:19]
	v_mfma_f32_16x16x32_bf16 v[16:19], v[242:245], v[64:67], v[72:75]
	v_mfma_f32_16x16x32_bf16 v[100:103], v[246:249], v[202:205], v[16:19]
	v_mfma_f32_16x16x32_bf16 v[16:19], v[210:213], v[218:221], v[68:71]
	v_mfma_f32_16x16x32_bf16 v[64:67], v[214:217], v[222:225], v[16:19]
	v_mfma_f32_16x16x32_bf16 v[16:19], v[242:245], v[218:221], v[186:189]
	v_mfma_f32_16x16x32_bf16 v[120:123], v[214:217], v[20:23], v[92:95]
	v_mfma_f32_16x16x32_bf16 v[68:71], v[246:249], v[222:225], v[16:19]
	s_setprio 0
	s_barrier
	ds_read_b128 v[92:95], v138 offset:0
	ds_read_b128 v[178:181], v138 offset:1024
	ds_read_b128 v[182:185], v138 offset:2048
	ds_read_b128 v[186:189], v138 offset:3072
	ds_read_b128 v[202:205], v138 offset:4096
	ds_read_b128 v[218:221], v138 offset:5120
	ds_read_b128 v[222:225], v138 offset:6144
	ds_read_b128 v[138:141], v138 offset:7168
	s_barrier
	s_waitcnt lgkmcnt(0)
	s_setprio 1
	v_mfma_f32_16x16x32_bf16 v[16:19], v[0:3], v[92:95], v[60:63]
	v_mfma_f32_16x16x32_bf16 v[72:75], v[4:7], v[178:181], v[16:19]
	v_mfma_f32_16x16x32_bf16 v[16:19], v[194:197], v[92:95], v[56:59]
	v_mfma_f32_16x16x32_bf16 v[76:79], v[198:201], v[178:181], v[16:19]
	v_mfma_f32_16x16x32_bf16 v[16:19], v[0:3], v[182:185], v[206:209]
	v_mfma_f32_16x16x32_bf16 v[40:43], v[4:7], v[186:189], v[16:19]
	v_mfma_f32_16x16x32_bf16 v[16:19], v[194:197], v[182:185], v[226:229]
	v_mfma_f32_16x16x32_bf16 v[44:47], v[198:201], v[186:189], v[16:19]
	v_mfma_f32_16x16x32_bf16 v[16:19], v[0:3], v[202:205], v[232:235]
	v_mfma_f32_16x16x32_bf16 v[0:3], v[0:3], v[222:225], v[158:161]
	v_mfma_f32_16x16x32_bf16 v[16:19], v[4:7], v[218:221], v[16:19]
	v_mfma_f32_16x16x32_bf16 v[20:23], v[194:197], v[202:205], v[238:241]
	v_mfma_f32_16x16x32_bf16 v[0:3], v[4:7], v[138:141], v[0:3]
	v_mfma_f32_16x16x32_bf16 v[4:7], v[194:197], v[222:225], v[162:165]
	v_mfma_f32_16x16x32_bf16 v[20:23], v[198:201], v[218:221], v[20:23]
	v_mfma_f32_16x16x32_bf16 v[4:7], v[198:201], v[138:141], v[4:7]
	s_setprio 0
	s_setprio 1
	v_mfma_f32_16x16x32_bf16 v[24:27], v[242:245], v[92:95], v[24:27]
	v_mfma_f32_16x16x32_bf16 v[28:31], v[210:213], v[92:95], v[28:31]
	v_mfma_f32_16x16x32_bf16 v[92:95], v[246:249], v[178:181], v[24:27]
	v_mfma_f32_16x16x32_bf16 v[24:27], v[210:213], v[182:185], v[166:169]
	v_mfma_f32_16x16x32_bf16 v[56:59], v[214:217], v[186:189], v[24:27]
	v_mfma_f32_16x16x32_bf16 v[24:27], v[242:245], v[182:185], v[170:173]
	v_mfma_f32_16x16x32_bf16 v[12:15], v[210:213], v[202:205], v[12:15]
	v_mfma_f32_16x16x32_bf16 v[8:11], v[242:245], v[202:205], v[8:11]
	v_mfma_f32_16x16x32_bf16 v[88:91], v[214:217], v[178:181], v[28:31]
	v_mfma_f32_16x16x32_bf16 v[60:63], v[246:249], v[186:189], v[24:27]
	v_mfma_f32_16x16x32_bf16 v[24:27], v[214:217], v[218:221], v[12:15]
	v_mfma_f32_16x16x32_bf16 v[28:31], v[246:249], v[218:221], v[8:11]
	v_mfma_f32_16x16x32_bf16 v[8:11], v[210:213], v[222:225], v[190:193]
	v_mfma_f32_16x16x32_bf16 v[12:15], v[242:245], v[222:225], v[142:145]
	v_mfma_f32_16x16x32_bf16 v[8:11], v[214:217], v[138:141], v[8:11]
	v_mfma_f32_16x16x32_bf16 v[12:15], v[246:249], v[138:141], v[12:15]
	s_setprio 0
	s_cmpk_lt_u32 s11, 0x100
	s_barrier
	s_cbranch_scc0 .LBB0_108
	s_barrier

.LBB0_127:
	s_waitcnt vmcnt(2)
	s_add_u32 s26, s26, 0x80
	s_addc_u32 s27, s27, 0
	s_and_b64 vcc, exec, s[38:39]
	v_mov_b32_e32 v8, v128
	s_barrier
	s_cbranch_vccnz .LBB0_129
	v_bfe_u32 v9, v134, 6, 2
	v_and_b32_e32 v0, 31, v4
	v_lshlrev_b32_e32 v1, 1, v4
	v_lshrrev_b32_e32 v8, 13, v6
	v_add_u32_e32 v9, v4, v9
	v_and_b32_e32 v1, 24, v1
	v_and_b32_e32 v8, 4, v8
	v_sub_u32_e32 v0, v9, v0
	v_add3_u32 v0, v0, v1, v8
	v_lshl_or_b32 v8, v0, 11, v2

.LBB0_141:
	ds_read_b128 v[148:151], v145 offset:0
	ds_read_b128 v[152:155], v145 offset:1024
	ds_read_b128 v[160:163], v145 offset:2048
	ds_read_b128 v[164:167], v145 offset:3072
	s_add_u32 s35, s1, s38
	s_addc_u32 s41, s26, s39
	s_add_u32 s40, s35, 0x80
	v_add_u32_e32 v158, 0xc000, v134
	s_addc_u32 s41, s41, 0
	v_readfirstlane_b32 s35, v158
	v_add_u32_e32 v159, 0xe000, v134
	v_lshl_add_u64 v[146:147], s[40:41], 0, v[128:129]
	s_mov_b32 m0, s35
	v_readfirstlane_b32 s35, v159
	ds_read_b128 v[168:171], v144 offset:0
	ds_read_b128 v[172:175], v144 offset:1024
	ds_read_b128 v[178:181], v144 offset:2048
	ds_read_b128 v[182:185], v144 offset:3072
	ds_read_b128 v[186:189], v144 offset:4096
	ds_read_b128 v[190:193], v144 offset:5120
	ds_read_b128 v[194:197], v144 offset:6144
	ds_read_b128 v[198:201], v144 offset:7168
	global_load_lds_dwordx4 v[146:147], off
	v_lshl_add_u64 v[146:147], s[40:41], 0, v[130:131]
	s_mov_b32 m0, s35
	s_nop 0
	global_load_lds_dwordx4 v[146:147], off
	ds_read_b128 v[202:205], v143 offset:0
	ds_read_b128 v[206:209], v143 offset:1024
	ds_read_b128 v[210:213], v143 offset:2048
	ds_read_b128 v[214:217], v143 offset:3072
	s_waitcnt vmcnt(8)
	s_waitcnt lgkmcnt(0)
	s_barrier
	s_waitcnt lgkmcnt(0)
	s_waitcnt lgkmcnt(0)
	s_setprio 1
	v_mfma_f32_16x16x32_bf16 v[124:127], v[148:151], v[168:171], v[124:127]
	v_mfma_f32_16x16x32_bf16 v[120:123], v[160:163], v[168:171], v[120:123]
	v_mfma_f32_16x16x32_bf16 v[116:119], v[148:151], v[178:181], v[116:119]
	v_mfma_f32_16x16x32_bf16 v[112:115], v[160:163], v[178:181], v[112:115]
	v_mfma_f32_16x16x32_bf16 v[108:111], v[148:151], v[186:189], v[108:111]
	v_mfma_f32_16x16x32_bf16 v[104:107], v[160:163], v[186:189], v[104:107]
	v_mfma_f32_16x16x32_bf16 v[100:103], v[148:151], v[194:197], v[100:103]
	v_mfma_f32_16x16x32_bf16 v[96:99], v[160:163], v[194:197], v[96:99]
	v_mfma_f32_16x16x32_bf16 v[124:127], v[152:155], v[172:175], v[124:127]
	v_mfma_f32_16x16x32_bf16 v[120:123], v[164:167], v[172:175], v[120:123]
	v_mfma_f32_16x16x32_bf16 v[116:119], v[152:155], v[182:185], v[116:119]
	v_mfma_f32_16x16x32_bf16 v[112:115], v[164:167], v[182:185], v[112:115]
	v_mfma_f32_16x16x32_bf16 v[108:111], v[152:155], v[190:193], v[108:111]
	v_mfma_f32_16x16x32_bf16 v[104:107], v[164:167], v[190:193], v[104:107]
	v_mfma_f32_16x16x32_bf16 v[100:103], v[152:155], v[198:201], v[100:103]
	v_mfma_f32_16x16x32_bf16 v[96:99], v[164:167], v[198:201], v[96:99]
	s_setprio 0
	s_waitcnt lgkmcnt(0)
	s_setprio 1
	v_mfma_f32_16x16x32_bf16 v[92:95], v[202:205], v[168:171], v[92:95]
	v_mfma_f32_16x16x32_bf16 v[88:91], v[210:213], v[168:171], v[88:91]
	v_mfma_f32_16x16x32_bf16 v[84:87], v[202:205], v[178:181], v[84:87]
	v_mfma_f32_16x16x32_bf16 v[80:83], v[210:213], v[178:181], v[80:83]
	v_mfma_f32_16x16x32_bf16 v[76:79], v[202:205], v[186:189], v[76:79]
	v_mfma_f32_16x16x32_bf16 v[72:75], v[210:213], v[186:189], v[72:75]
	v_mfma_f32_16x16x32_bf16 v[68:71], v[202:205], v[194:197], v[68:71]
	v_mfma_f32_16x16x32_bf16 v[64:67], v[210:213], v[194:197], v[64:67]
	v_mfma_f32_16x16x32_bf16 v[92:95], v[206:209], v[172:175], v[92:95]
	v_mfma_f32_16x16x32_bf16 v[88:91], v[214:217], v[172:175], v[88:91]
	v_mfma_f32_16x16x32_bf16 v[84:87], v[206:209], v[182:185], v[84:87]
	v_mfma_f32_16x16x32_bf16 v[80:83], v[214:217], v[182:185], v[80:83]
	v_mfma_f32_16x16x32_bf16 v[76:79], v[206:209], v[190:193], v[76:79]
	v_mfma_f32_16x16x32_bf16 v[72:75], v[214:217], v[190:193], v[72:75]
	v_mfma_f32_16x16x32_bf16 v[68:71], v[206:209], v[198:201], v[68:71]
	v_mfma_f32_16x16x32_bf16 v[64:67], v[214:217], v[198:201], v[64:67]
	s_setprio 0
	s_barrier
	s_add_u32 s35, s27, s38
	s_addc_u32 s42, s28, s39
	s_add_u32 s40, s35, 0x100
	v_add_u32_e32 v146, 0x10000, v134
	s_addc_u32 s41, s42, 0
	v_readfirstlane_b32 s43, v146
	v_lshl_add_u64 v[156:157], s[40:41], 0, v[176:177]
	s_mov_b32 m0, s43
	v_add_u32_e32 v147, 0x12000, v134
	global_load_lds_dwordx4 v[156:157], off
	v_lshl_add_u64 v[156:157], s[40:41], 0, v[132:133]
	v_readfirstlane_b32 s40, v147
	s_mov_b32 m0, s40
	s_nop 0
	global_load_lds_dwordx4 v[156:157], off
	s_add_u32 s43, s2, s38
	s_addc_u32 s45, s3, s39
	s_add_u32 s40, s43, 0x100
	s_addc_u32 s41, s45, 0
	v_readfirstlane_b32 s48, v134
	v_lshl_add_u64 v[156:157], s[40:41], 0, v[128:129]
	s_mov_b32 m0, s48
	ds_read_b128 v[168:171], v142 offset:0
	ds_read_b128 v[172:175], v142 offset:1024
	ds_read_b128 v[178:181], v142 offset:2048
	ds_read_b128 v[182:185], v142 offset:3072
	ds_read_b128 v[186:189], v142 offset:4096
	ds_read_b128 v[190:193], v142 offset:5120
	ds_read_b128 v[194:197], v142 offset:6144
	ds_read_b128 v[198:201], v142 offset:7168
	global_load_lds_dwordx4 v[156:157], off
	v_lshl_add_u64 v[156:157], s[40:41], 0, v[130:131]
	v_readfirstlane_b32 s40, v135
	s_mov_b32 m0, s40
	s_nop 0
	global_load_lds_dwordx4 v[156:157], off
	s_add_u32 s48, s20, s38
	s_addc_u32 s49, s21, s39
	s_add_u32 s40, s48, 0x100
	v_add_u32_e32 v226, 0x14000, v134
	s_addc_u32 s41, s49, 0
	v_readfirstlane_b32 s51, v226
	v_lshl_add_u64 v[228:229], s[40:41], 0, v[176:177]
	s_mov_b32 m0, s51
	v_add_u32_e32 v227, 0x16000, v134
	global_load_lds_dwordx4 v[228:229], off
	v_lshl_add_u64 v[228:229], s[40:41], 0, v[132:133]
	v_readfirstlane_b32 s40, v227
	s_mov_b32 m0, s40
	s_nop 0
	global_load_lds_dwordx4 v[228:229], off
	s_waitcnt vmcnt(8)
	s_waitcnt lgkmcnt(0)
	s_barrier
	s_waitcnt lgkmcnt(0)
	s_setprio 1
	v_mfma_f32_16x16x32_bf16 v[60:63], v[148:151], v[168:171], v[60:63]
	v_mfma_f32_16x16x32_bf16 v[56:59], v[160:163], v[168:171], v[56:59]
	v_mfma_f32_16x16x32_bf16 v[52:55], v[148:151], v[178:181], v[52:55]
	v_mfma_f32_16x16x32_bf16 v[48:51], v[160:163], v[178:181], v[48:51]
	v_mfma_f32_16x16x32_bf16 v[44:47], v[148:151], v[186:189], v[44:47]
	v_mfma_f32_16x16x32_bf16 v[40:43], v[160:163], v[186:189], v[40:43]
	v_mfma_f32_16x16x32_bf16 v[36:39], v[148:151], v[194:197], v[36:39]
	v_mfma_f32_16x16x32_bf16 v[32:35], v[160:163], v[194:197], v[32:35]
	v_mfma_f32_16x16x32_bf16 v[60:63], v[152:155], v[172:175], v[60:63]
	v_mfma_f32_16x16x32_bf16 v[56:59], v[164:167], v[172:175], v[56:59]
	v_mfma_f32_16x16x32_bf16 v[52:55], v[152:155], v[182:185], v[52:55]
	v_mfma_f32_16x16x32_bf16 v[48:51], v[164:167], v[182:185], v[48:51]
	v_mfma_f32_16x16x32_bf16 v[44:47], v[152:155], v[190:193], v[44:47]
	v_mfma_f32_16x16x32_bf16 v[40:43], v[164:167], v[190:193], v[40:43]
	v_mfma_f32_16x16x32_bf16 v[36:39], v[152:155], v[198:201], v[36:39]
	v_mfma_f32_16x16x32_bf16 v[32:35], v[164:167], v[198:201], v[32:35]
	s_setprio 0
	s_setprio 1
	v_mfma_f32_16x16x32_bf16 v[28:31], v[202:205], v[168:171], v[28:31]
	v_mfma_f32_16x16x32_bf16 v[24:27], v[210:213], v[168:171], v[24:27]
	v_mfma_f32_16x16x32_bf16 v[20:23], v[202:205], v[178:181], v[20:23]
	v_mfma_f32_16x16x32_bf16 v[16:19], v[210:213], v[178:181], v[16:19]
	v_mfma_f32_16x16x32_bf16 v[12:15], v[202:205], v[186:189], v[12:15]
	v_mfma_f32_16x16x32_bf16 v[8:11], v[210:213], v[186:189], v[8:11]
	v_mfma_f32_16x16x32_bf16 v[4:7], v[202:205], v[194:197], v[4:7]
	v_mfma_f32_16x16x32_bf16 v[0:3], v[210:213], v[194:197], v[0:3]
	v_mfma_f32_16x16x32_bf16 v[28:31], v[206:209], v[172:175], v[28:31]
	v_mfma_f32_16x16x32_bf16 v[24:27], v[214:217], v[172:175], v[24:27]
	v_mfma_f32_16x16x32_bf16 v[20:23], v[206:209], v[182:185], v[20:23]
	v_mfma_f32_16x16x32_bf16 v[16:19], v[214:217], v[182:185], v[16:19]
	v_mfma_f32_16x16x32_bf16 v[12:15], v[206:209], v[190:193], v[12:15]
	v_mfma_f32_16x16x32_bf16 v[8:11], v[214:217], v[190:193], v[8:11]
	v_mfma_f32_16x16x32_bf16 v[4:7], v[206:209], v[198:201], v[4:7]
	v_mfma_f32_16x16x32_bf16 v[0:3], v[214:217], v[198:201], v[0:3]
	s_setprio 0
	s_barrier
	ds_read_b128 v[160:163], v141 offset:0
	ds_read_b128 v[164:167], v141 offset:1024
	ds_read_b128 v[168:171], v141 offset:2048
	ds_read_b128 v[172:175], v141 offset:3072
	s_add_u32 s40, s29, s38
	v_add_u32_e32 v150, 0x4000, v134
	s_addc_u32 s41, s30, s39
	v_readfirstlane_b32 s51, v150
	v_lshl_add_u64 v[152:153], s[40:41], 0, v[128:129]
	s_mov_b32 m0, s51
	v_add_u32_e32 v151, 0x6000, v134
	ds_read_b128 v[154:157], v140 offset:0
	ds_read_b128 v[178:181], v140 offset:1024
	ds_read_b128 v[182:185], v140 offset:2048
	ds_read_b128 v[186:189], v140 offset:3072
	ds_read_b128 v[190:193], v140 offset:4096
	ds_read_b128 v[194:197], v140 offset:5120
	ds_read_b128 v[198:201], v140 offset:6144
	ds_read_b128 v[202:205], v140 offset:7168
	global_load_lds_dwordx4 v[152:153], off
	v_lshl_add_u64 v[152:153], s[40:41], 0, v[130:131]
	v_readfirstlane_b32 s40, v151
	s_mov_b32 m0, s40
	s_nop 0
	global_load_lds_dwordx4 v[152:153], off
	ds_read_b128 v[206:209], v139 offset:0
	ds_read_b128 v[210:213], v139 offset:1024
	ds_read_b128 v[214:217], v139 offset:2048
	ds_read_b128 v[218:221], v139 offset:3072
	s_waitcnt vmcnt(8)
	s_waitcnt lgkmcnt(0)
	s_barrier
	s_waitcnt lgkmcnt(0)
	s_waitcnt lgkmcnt(0)
	s_setprio 1
	v_mfma_f32_16x16x32_bf16 v[124:127], v[160:163], v[154:157], v[124:127]
	v_mfma_f32_16x16x32_bf16 v[120:123], v[168:171], v[154:157], v[120:123]
	v_mfma_f32_16x16x32_bf16 v[116:119], v[160:163], v[182:185], v[116:119]
	v_mfma_f32_16x16x32_bf16 v[112:115], v[168:171], v[182:185], v[112:115]
	v_mfma_f32_16x16x32_bf16 v[108:111], v[160:163], v[190:193], v[108:111]
	v_mfma_f32_16x16x32_bf16 v[104:107], v[168:171], v[190:193], v[104:107]
	v_mfma_f32_16x16x32_bf16 v[100:103], v[160:163], v[198:201], v[100:103]
	v_mfma_f32_16x16x32_bf16 v[96:99], v[168:171], v[198:201], v[96:99]
	v_mfma_f32_16x16x32_bf16 v[124:127], v[164:167], v[178:181], v[124:127]
	v_mfma_f32_16x16x32_bf16 v[120:123], v[172:175], v[178:181], v[120:123]
	v_mfma_f32_16x16x32_bf16 v[116:119], v[164:167], v[186:189], v[116:119]
	v_mfma_f32_16x16x32_bf16 v[112:115], v[172:175], v[186:189], v[112:115]
	v_mfma_f32_16x16x32_bf16 v[108:111], v[164:167], v[194:197], v[108:111]
	v_mfma_f32_16x16x32_bf16 v[104:107], v[172:175], v[194:197], v[104:107]
	v_mfma_f32_16x16x32_bf16 v[100:103], v[164:167], v[202:205], v[100:103]
	v_mfma_f32_16x16x32_bf16 v[96:99], v[172:175], v[202:205], v[96:99]
	s_setprio 0
	s_waitcnt lgkmcnt(0)
	s_setprio 1
	v_mfma_f32_16x16x32_bf16 v[92:95], v[206:209], v[154:157], v[92:95]
	v_mfma_f32_16x16x32_bf16 v[88:91], v[214:217], v[154:157], v[88:91]
	v_mfma_f32_16x16x32_bf16 v[84:87], v[206:209], v[182:185], v[84:87]
	v_mfma_f32_16x16x32_bf16 v[80:83], v[214:217], v[182:185], v[80:83]
	v_mfma_f32_16x16x32_bf16 v[76:79], v[206:209], v[190:193], v[76:79]
	v_mfma_f32_16x16x32_bf16 v[72:75], v[214:217], v[190:193], v[72:75]
	v_mfma_f32_16x16x32_bf16 v[68:71], v[206:209], v[198:201], v[68:71]
	v_mfma_f32_16x16x32_bf16 v[64:67], v[214:217], v[198:201], v[64:67]
	v_mfma_f32_16x16x32_bf16 v[92:95], v[210:213], v[178:181], v[92:95]
	v_mfma_f32_16x16x32_bf16 v[88:91], v[218:221], v[178:181], v[88:91]
	v_mfma_f32_16x16x32_bf16 v[84:87], v[210:213], v[186:189], v[84:87]
	v_mfma_f32_16x16x32_bf16 v[80:83], v[218:221], v[186:189], v[80:83]
	v_mfma_f32_16x16x32_bf16 v[76:79], v[210:213], v[194:197], v[76:79]
	v_mfma_f32_16x16x32_bf16 v[72:75], v[218:221], v[194:197], v[72:75]
	v_mfma_f32_16x16x32_bf16 v[68:71], v[210:213], v[202:205], v[68:71]
	v_mfma_f32_16x16x32_bf16 v[64:67], v[218:221], v[202:205], v[64:67]
	s_setprio 0
	s_barrier
	s_add_u32 s40, s35, 0x180
	v_add_u32_e32 v152, 0x18000, v134
	s_addc_u32 s41, s42, 0
	v_readfirstlane_b32 s35, v152
	v_add_u32_e32 v153, 0x1a000, v134
	v_lshl_add_u64 v[222:223], s[40:41], 0, v[176:177]
	s_mov_b32 m0, s35
	v_readfirstlane_b32 s35, v153
	global_load_lds_dwordx4 v[222:223], off
	v_lshl_add_u64 v[222:223], s[40:41], 0, v[132:133]
	s_mov_b32 m0, s35
	s_nop 0
	global_load_lds_dwordx4 v[222:223], off
	s_add_u32 s40, s43, 0x180
	v_add_u32_e32 v154, 0x8000, v134
	s_addc_u32 s41, s45, 0
	v_readfirstlane_b32 s35, v154
	v_add_u32_e32 v155, 0xa000, v134
	v_lshl_add_u64 v[156:157], s[40:41], 0, v[128:129]
	s_mov_b32 m0, s35
	v_readfirstlane_b32 s35, v155
	ds_read_b128 v[178:181], v138 offset:0
	ds_read_b128 v[182:185], v138 offset:1024
	ds_read_b128 v[186:189], v138 offset:2048
	ds_read_b128 v[190:193], v138 offset:3072
	ds_read_b128 v[194:197], v138 offset:4096
	ds_read_b128 v[198:201], v138 offset:5120
	ds_read_b128 v[202:205], v138 offset:6144
	ds_read_b128 v[222:225], v138 offset:7168
	global_load_lds_dwordx4 v[156:157], off
	v_lshl_add_u64 v[156:157], s[40:41], 0, v[130:131]
	s_mov_b32 m0, s35
	s_nop 0
	global_load_lds_dwordx4 v[156:157], off
	s_add_u32 s40, s48, 0x180
	v_add_u32_e32 v156, 0x1c000, v134
	s_addc_u32 s41, s49, 0
	v_readfirstlane_b32 s35, v156
	v_add_u32_e32 v157, 0x1e000, v134
	v_lshl_add_u64 v[226:227], s[40:41], 0, v[176:177]
	s_mov_b32 m0, s35
	v_readfirstlane_b32 s35, v157
	global_load_lds_dwordx4 v[226:227], off
	v_lshl_add_u64 v[226:227], s[40:41], 0, v[132:133]
	s_mov_b32 m0, s35
	s_nop 0
	global_load_lds_dwordx4 v[226:227], off
	s_waitcnt vmcnt(8)
	s_waitcnt lgkmcnt(0)
	s_barrier
	s_waitcnt lgkmcnt(0)
	s_setprio 1
	v_mfma_f32_16x16x32_bf16 v[60:63], v[160:163], v[178:181], v[60:63]
	v_mfma_f32_16x16x32_bf16 v[56:59], v[168:171], v[178:181], v[56:59]
	v_mfma_f32_16x16x32_bf16 v[52:55], v[160:163], v[186:189], v[52:55]
	v_mfma_f32_16x16x32_bf16 v[48:51], v[168:171], v[186:189], v[48:51]
	v_mfma_f32_16x16x32_bf16 v[44:47], v[160:163], v[194:197], v[44:47]
	v_mfma_f32_16x16x32_bf16 v[40:43], v[168:171], v[194:197], v[40:43]
	v_mfma_f32_16x16x32_bf16 v[36:39], v[160:163], v[202:205], v[36:39]
	v_mfma_f32_16x16x32_bf16 v[32:35], v[168:171], v[202:205], v[32:35]
	v_mfma_f32_16x16x32_bf16 v[60:63], v[164:167], v[182:185], v[60:63]
	v_mfma_f32_16x16x32_bf16 v[56:59], v[172:175], v[182:185], v[56:59]
	v_mfma_f32_16x16x32_bf16 v[52:55], v[164:167], v[190:193], v[52:55]
	v_mfma_f32_16x16x32_bf16 v[48:51], v[172:175], v[190:193], v[48:51]
	v_mfma_f32_16x16x32_bf16 v[44:47], v[164:167], v[198:201], v[44:47]
	v_mfma_f32_16x16x32_bf16 v[40:43], v[172:175], v[198:201], v[40:43]
	v_mfma_f32_16x16x32_bf16 v[36:39], v[164:167], v[222:225], v[36:39]
	v_mfma_f32_16x16x32_bf16 v[32:35], v[172:175], v[222:225], v[32:35]
	s_setprio 0
	s_setprio 1
	v_mfma_f32_16x16x32_bf16 v[28:31], v[206:209], v[178:181], v[28:31]
	v_mfma_f32_16x16x32_bf16 v[24:27], v[214:217], v[178:181], v[24:27]
	v_mfma_f32_16x16x32_bf16 v[20:23], v[206:209], v[186:189], v[20:23]
	v_mfma_f32_16x16x32_bf16 v[16:19], v[214:217], v[186:189], v[16:19]
	v_mfma_f32_16x16x32_bf16 v[12:15], v[206:209], v[194:197], v[12:15]
	v_mfma_f32_16x16x32_bf16 v[8:11], v[214:217], v[194:197], v[8:11]
	v_mfma_f32_16x16x32_bf16 v[4:7], v[206:209], v[202:205], v[4:7]
	v_mfma_f32_16x16x32_bf16 v[0:3], v[214:217], v[202:205], v[0:3]
	v_mfma_f32_16x16x32_bf16 v[28:31], v[210:213], v[182:185], v[28:31]
	v_mfma_f32_16x16x32_bf16 v[24:27], v[218:221], v[182:185], v[24:27]
	v_mfma_f32_16x16x32_bf16 v[20:23], v[210:213], v[190:193], v[20:23]
	v_mfma_f32_16x16x32_bf16 v[16:19], v[218:221], v[190:193], v[16:19]
	v_mfma_f32_16x16x32_bf16 v[12:15], v[210:213], v[198:201], v[12:15]
	v_mfma_f32_16x16x32_bf16 v[8:11], v[218:221], v[198:201], v[8:11]
	v_mfma_f32_16x16x32_bf16 v[4:7], v[210:213], v[222:225], v[4:7]
	v_mfma_f32_16x16x32_bf16 v[0:3], v[218:221], v[222:225], v[0:3]
	s_setprio 0
	s_add_i32 s31, s31, 2
	s_add_u32 s38, s38, 0x100
	s_addc_u32 s39, s39, 0
	s_cmp_gt_u32 s31, 11
	s_barrier
	s_cbranch_scc0 .LBB0_141
	v_add_u32_e32 v158, 0xc000, v134
	v_add_u32_e32 v159, 0xe000, v134
	v_add_u32_e32 v146, 0x10000, v134
	v_add_u32_e32 v147, 0x12000, v134
	v_add_u32_e32 v148, 0x14000, v134
	v_add_u32_e32 v149, 0x16000, v134
	v_add_u32_e32 v150, 0x4000, v134
	v_add_u32_e32 v151, 0x6000, v134
	v_add_u32_e32 v152, 0x18000, v134
	v_add_u32_e32 v153, 0x1a000, v134
	v_add_u32_e32 v154, 0x8000, v134
	v_add_u32_e32 v155, 0xa000, v134
	v_add_u32_e32 v156, 0x1c000, v134
	v_add_u32_e32 v157, 0x1e000, v134
	s_add_u32 s2, s1, 0x780
	s_addc_u32 s3, s26, 0
	v_readfirstlane_b32 s1, v158
	v_lshl_add_u64 v[132:133], s[2:3], 0, v[128:129]
	s_mov_b32 m0, s1
	v_readfirstlane_b32 s1, v159
	ds_read_b128 v[160:163], v145 offset:0
	ds_read_b128 v[164:167], v145 offset:1024
	ds_read_b128 v[168:171], v145 offset:2048
	ds_read_b128 v[172:175], v145 offset:3072
	ds_read_b128 v[178:181], v144 offset:0
	ds_read_b128 v[182:185], v144 offset:1024
	ds_read_b128 v[190:193], v144 offset:2048
	ds_read_b128 v[194:197], v144 offset:3072
	ds_read_b128 v[198:201], v144 offset:4096
	ds_read_b128 v[202:205], v144 offset:5120
	ds_read_b128 v[206:209], v144 offset:6144
	ds_read_b128 v[210:213], v144 offset:7168
	global_load_lds_dwordx4 v[132:133], off
	v_lshl_add_u64 v[132:133], s[2:3], 0, v[130:131]
	s_mov_b32 m0, s1
	s_nop 0
	global_load_lds_dwordx4 v[132:133], off
	s_waitcnt vmcnt(10)
	s_barrier
	s_waitcnt lgkmcnt(0)
	s_waitcnt lgkmcnt(0)
	s_setprio 1
	v_mfma_f32_16x16x32_bf16 v[124:127], v[160:163], v[178:181], v[124:127]
	v_mfma_f32_16x16x32_bf16 v[116:119], v[160:163], v[190:193], v[116:119]
	v_mfma_f32_16x16x32_bf16 v[108:111], v[160:163], v[198:201], v[108:111]
	v_mfma_f32_16x16x32_bf16 v[100:103], v[160:163], v[206:209], v[100:103]
	v_mfma_f32_16x16x32_bf16 v[124:127], v[164:167], v[182:185], v[124:127]
	v_mfma_f32_16x16x32_bf16 v[120:123], v[168:171], v[178:181], v[120:123]
	v_mfma_f32_16x16x32_bf16 v[116:119], v[164:167], v[194:197], v[116:119]
	v_mfma_f32_16x16x32_bf16 v[112:115], v[168:171], v[190:193], v[112:115]
	v_mfma_f32_16x16x32_bf16 v[108:111], v[164:167], v[202:205], v[108:111]
	v_mfma_f32_16x16x32_bf16 v[104:107], v[168:171], v[198:201], v[104:107]
	v_mfma_f32_16x16x32_bf16 v[100:103], v[164:167], v[210:213], v[100:103]
	v_mfma_f32_16x16x32_bf16 v[96:99], v[168:171], v[206:209], v[96:99]
	v_mfma_f32_16x16x32_bf16 v[214:217], v[172:175], v[182:185], v[120:123]
	v_mfma_f32_16x16x32_bf16 v[218:221], v[172:175], v[194:197], v[112:115]
	v_mfma_f32_16x16x32_bf16 v[222:225], v[172:175], v[202:205], v[104:107]
	v_mfma_f32_16x16x32_bf16 v[226:229], v[172:175], v[210:213], v[96:99]
	s_setprio 0
	s_barrier
	ds_read_b128 v[96:99], v143 offset:0
	ds_read_b128 v[104:107], v143 offset:1024
	ds_read_b128 v[112:115], v143 offset:2048
	ds_read_b128 v[120:123], v143 offset:3072
	s_waitcnt vmcnt(8)
	s_barrier
	s_waitcnt lgkmcnt(0)
	s_setprio 1
	v_mfma_f32_16x16x32_bf16 v[92:95], v[96:99], v[178:181], v[92:95]
	v_mfma_f32_16x16x32_bf16 v[88:91], v[112:115], v[178:181], v[88:91]
	v_mfma_f32_16x16x32_bf16 v[84:87], v[96:99], v[190:193], v[84:87]
	v_mfma_f32_16x16x32_bf16 v[80:83], v[112:115], v[190:193], v[80:83]
	v_mfma_f32_16x16x32_bf16 v[76:79], v[96:99], v[198:201], v[76:79]
	v_mfma_f32_16x16x32_bf16 v[72:75], v[112:115], v[198:201], v[72:75]
	v_mfma_f32_16x16x32_bf16 v[68:71], v[96:99], v[206:209], v[68:71]
	v_mfma_f32_16x16x32_bf16 v[64:67], v[112:115], v[206:209], v[64:67]
	v_mfma_f32_16x16x32_bf16 v[92:95], v[104:107], v[182:185], v[92:95]
	v_mfma_f32_16x16x32_bf16 v[88:91], v[120:123], v[182:185], v[88:91]
	v_mfma_f32_16x16x32_bf16 v[84:87], v[104:107], v[194:197], v[84:87]
	v_mfma_f32_16x16x32_bf16 v[80:83], v[120:123], v[194:197], v[80:83]
	v_mfma_f32_16x16x32_bf16 v[76:79], v[104:107], v[202:205], v[76:79]
	v_mfma_f32_16x16x32_bf16 v[72:75], v[120:123], v[202:205], v[72:75]
	v_mfma_f32_16x16x32_bf16 v[68:71], v[104:107], v[210:213], v[68:71]
	v_mfma_f32_16x16x32_bf16 v[64:67], v[120:123], v[210:213], v[64:67]
	s_setprio 0
	s_barrier
	ds_read_b128 v[178:181], v142 offset:0
	ds_read_b128 v[182:185], v142 offset:1024
	ds_read_b128 v[190:193], v142 offset:2048
	ds_read_b128 v[194:197], v142 offset:3072
	ds_read_b128 v[198:201], v142 offset:4096
	ds_read_b128 v[202:205], v142 offset:5120
	ds_read_b128 v[206:209], v142 offset:6144
	ds_read_b128 v[142:145], v142 offset:7168
	s_waitcnt vmcnt(4)
	s_barrier
	s_waitcnt lgkmcnt(0)
	s_setprio 1
	v_mfma_f32_16x16x32_bf16 v[60:63], v[160:163], v[178:181], v[60:63]
	v_mfma_f32_16x16x32_bf16 v[210:213], v[164:167], v[182:185], v[60:63]
	v_mfma_f32_16x16x32_bf16 v[56:59], v[168:171], v[178:181], v[56:59]
	v_mfma_f32_16x16x32_bf16 v[52:55], v[160:163], v[190:193], v[52:55]
	v_mfma_f32_16x16x32_bf16 v[48:51], v[168:171], v[190:193], v[48:51]
	v_mfma_f32_16x16x32_bf16 v[44:47], v[160:163], v[198:201], v[44:47]
	v_mfma_f32_16x16x32_bf16 v[40:43], v[168:171], v[198:201], v[40:43]
	v_mfma_f32_16x16x32_bf16 v[36:39], v[160:163], v[206:209], v[36:39]
	v_mfma_f32_16x16x32_bf16 v[32:35], v[168:171], v[206:209], v[32:35]
	v_mfma_f32_16x16x32_bf16 v[238:241], v[172:175], v[182:185], v[56:59]
	v_mfma_f32_16x16x32_bf16 v[242:245], v[164:167], v[194:197], v[52:55]
	v_mfma_f32_16x16x32_bf16 v[246:249], v[172:175], v[194:197], v[48:51]
	v_mfma_f32_16x16x32_bf16 v[232:235], v[164:167], v[202:205], v[44:47]
	v_mfma_f32_16x16x32_bf16 v[186:189], v[172:175], v[202:205], v[40:43]
	v_mfma_f32_16x16x32_bf16 v[158:161], v[164:167], v[142:145], v[36:39]
	v_mfma_f32_16x16x32_bf16 v[162:165], v[172:175], v[142:145], v[32:35]
	s_setprio 0
	s_setprio 1
	v_mfma_f32_16x16x32_bf16 v[28:31], v[96:99], v[178:181], v[28:31]
	v_mfma_f32_16x16x32_bf16 v[20:23], v[96:99], v[190:193], v[20:23]
	v_mfma_f32_16x16x32_bf16 v[12:15], v[96:99], v[198:201], v[12:15]
	v_mfma_f32_16x16x32_bf16 v[4:7], v[96:99], v[206:209], v[4:7]
	v_mfma_f32_16x16x32_bf16 v[28:31], v[104:107], v[182:185], v[28:31]
	v_mfma_f32_16x16x32_bf16 v[24:27], v[112:115], v[178:181], v[24:27]
	v_mfma_f32_16x16x32_bf16 v[20:23], v[104:107], v[194:197], v[20:23]
	v_mfma_f32_16x16x32_bf16 v[16:19], v[112:115], v[190:193], v[16:19]
	v_mfma_f32_16x16x32_bf16 v[12:15], v[104:107], v[202:205], v[12:15]
	v_mfma_f32_16x16x32_bf16 v[8:11], v[112:115], v[198:201], v[8:11]
	v_mfma_f32_16x16x32_bf16 v[4:7], v[104:107], v[142:145], v[4:7]
	v_mfma_f32_16x16x32_bf16 v[0:3], v[112:115], v[206:209], v[0:3]
	v_mfma_f32_16x16x32_bf16 v[166:169], v[120:123], v[182:185], v[24:27]
	v_mfma_f32_16x16x32_bf16 v[170:173], v[120:123], v[194:197], v[16:19]
	v_mfma_f32_16x16x32_bf16 v[178:181], v[120:123], v[202:205], v[8:11]
	v_mfma_f32_16x16x32_bf16 v[142:145], v[120:123], v[142:145], v[0:3]
	s_setprio 0
	s_barrier
	ds_read_b128 v[0:3], v141 offset:0
	ds_read_b128 v[8:11], v141 offset:1024
	ds_read_b128 v[16:19], v141 offset:2048
	ds_read_b128 v[24:27], v141 offset:3072
	ds_read_b128 v[32:35], v140 offset:0
	ds_read_b128 v[36:39], v140 offset:1024
	ds_read_b128 v[40:43], v140 offset:2048
	ds_read_b128 v[44:47], v140 offset:3072
	ds_read_b128 v[182:185], v140 offset:4096
	ds_read_b128 v[190:193], v140 offset:5120
	ds_read_b128 v[194:197], v140 offset:6144
	ds_read_b128 v[198:201], v140 offset:7168
	s_waitcnt vmcnt(2)
	s_barrier
	s_waitcnt lgkmcnt(0)
	s_waitcnt lgkmcnt(0)
	s_setprio 1
	v_mfma_f32_16x16x32_bf16 v[48:51], v[0:3], v[32:35], v[124:127]
	v_mfma_f32_16x16x32_bf16 v[120:123], v[8:11], v[36:39], v[48:51]
	v_mfma_f32_16x16x32_bf16 v[48:51], v[16:19], v[32:35], v[214:217]
	v_mfma_f32_16x16x32_bf16 v[124:127], v[24:27], v[36:39], v[48:51]
	v_mfma_f32_16x16x32_bf16 v[48:51], v[0:3], v[40:43], v[116:119]
	v_mfma_f32_16x16x32_bf16 v[112:115], v[8:11], v[44:47], v[48:51]
	v_mfma_f32_16x16x32_bf16 v[48:51], v[16:19], v[40:43], v[218:221]
	v_mfma_f32_16x16x32_bf16 v[116:119], v[24:27], v[44:47], v[48:51]
	v_mfma_f32_16x16x32_bf16 v[48:51], v[0:3], v[182:185], v[108:111]
	v_mfma_f32_16x16x32_bf16 v[104:107], v[8:11], v[190:193], v[48:51]
	v_mfma_f32_16x16x32_bf16 v[48:51], v[16:19], v[182:185], v[222:225]
	v_mfma_f32_16x16x32_bf16 v[108:111], v[24:27], v[190:193], v[48:51]
	v_mfma_f32_16x16x32_bf16 v[48:51], v[0:3], v[194:197], v[100:103]
	v_mfma_f32_16x16x32_bf16 v[96:99], v[8:11], v[198:201], v[48:51]
	v_mfma_f32_16x16x32_bf16 v[48:51], v[16:19], v[194:197], v[226:229]
	v_mfma_f32_16x16x32_bf16 v[100:103], v[24:27], v[198:201], v[48:51]
	s_setprio 0
	s_barrier
	ds_read_b128 v[202:205], v139 offset:0
	ds_read_b128 v[206:209], v139 offset:1024
	ds_read_b128 v[214:217], v139 offset:2048
	ds_read_b128 v[218:221], v139 offset:3072
	s_waitcnt vmcnt(0)
	s_barrier
	s_waitcnt lgkmcnt(0)
	s_setprio 1
	v_mfma_f32_16x16x32_bf16 v[48:51], v[202:205], v[32:35], v[92:95]
	v_mfma_f32_16x16x32_bf16 v[32:35], v[214:217], v[32:35], v[88:91]
	v_mfma_f32_16x16x32_bf16 v[60:63], v[218:221], v[36:39], v[32:35]
	v_mfma_f32_16x16x32_bf16 v[32:35], v[202:205], v[40:43], v[84:87]
	v_mfma_f32_16x16x32_bf16 v[56:59], v[206:209], v[44:47], v[32:35]
	v_mfma_f32_16x16x32_bf16 v[32:35], v[214:217], v[40:43], v[80:83]
	v_mfma_f32_16x16x32_bf16 v[52:55], v[218:221], v[44:47], v[32:35]
	v_mfma_f32_16x16x32_bf16 v[32:35], v[202:205], v[182:185], v[76:79]
	v_mfma_f32_16x16x32_bf16 v[92:95], v[206:209], v[36:39], v[48:51]
	v_mfma_f32_16x16x32_bf16 v[48:51], v[206:209], v[190:193], v[32:35]
	v_mfma_f32_16x16x32_bf16 v[32:35], v[214:217], v[182:185], v[72:75]
	v_mfma_f32_16x16x32_bf16 v[44:47], v[218:221], v[190:193], v[32:35]
	v_mfma_f32_16x16x32_bf16 v[32:35], v[202:205], v[194:197], v[68:71]
	v_mfma_f32_16x16x32_bf16 v[36:39], v[214:217], v[194:197], v[64:67]
	v_mfma_f32_16x16x32_bf16 v[40:43], v[206:209], v[198:201], v[32:35]
	v_mfma_f32_16x16x32_bf16 v[36:39], v[218:221], v[198:201], v[36:39]
	s_setprio 0
	s_barrier
	ds_read_b128 v[182:185], v138 offset:0
	ds_read_b128 v[190:193], v138 offset:1024
	ds_read_b128 v[194:197], v138 offset:2048
	ds_read_b128 v[198:201], v138 offset:3072
	ds_read_b128 v[222:225], v138 offset:4096
	ds_read_b128 v[226:229], v138 offset:5120
	ds_read_b128 v[32:35], v138 offset:6144
	ds_read_b128 v[138:141], v138 offset:7168
	s_barrier
	s_waitcnt lgkmcnt(0)
	s_setprio 1
	v_mfma_f32_16x16x32_bf16 v[64:67], v[0:3], v[182:185], v[210:213]
	v_mfma_f32_16x16x32_bf16 v[88:91], v[8:11], v[190:193], v[64:67]
	v_mfma_f32_16x16x32_bf16 v[64:67], v[16:19], v[182:185], v[238:241]
	v_mfma_f32_16x16x32_bf16 v[210:213], v[24:27], v[190:193], v[64:67]
	v_mfma_f32_16x16x32_bf16 v[64:67], v[0:3], v[194:197], v[242:245]
	v_mfma_f32_16x16x32_bf16 v[80:83], v[8:11], v[198:201], v[64:67]
	v_mfma_f32_16x16x32_bf16 v[64:67], v[16:19], v[194:197], v[246:249]
	v_mfma_f32_16x16x32_bf16 v[84:87], v[24:27], v[198:201], v[64:67]
	v_mfma_f32_16x16x32_bf16 v[64:67], v[0:3], v[222:225], v[232:235]
	v_mfma_f32_16x16x32_bf16 v[72:75], v[8:11], v[226:229], v[64:67]
	v_mfma_f32_16x16x32_bf16 v[64:67], v[16:19], v[222:225], v[186:189]
	v_mfma_f32_16x16x32_bf16 v[0:3], v[0:3], v[32:35], v[158:161]
	v_mfma_f32_16x16x32_bf16 v[76:79], v[24:27], v[226:229], v[64:67]
	v_mfma_f32_16x16x32_bf16 v[64:67], v[8:11], v[138:141], v[0:3]
	v_mfma_f32_16x16x32_bf16 v[0:3], v[16:19], v[32:35], v[162:165]
	v_mfma_f32_16x16x32_bf16 v[68:71], v[24:27], v[138:141], v[0:3]
	s_setprio 0
	s_setprio 1
	v_mfma_f32_16x16x32_bf16 v[0:3], v[202:205], v[182:185], v[28:31]
	v_mfma_f32_16x16x32_bf16 v[24:27], v[206:209], v[190:193], v[0:3]
	v_mfma_f32_16x16x32_bf16 v[0:3], v[214:217], v[182:185], v[166:169]
	v_mfma_f32_16x16x32_bf16 v[28:31], v[218:221], v[190:193], v[0:3]
	v_mfma_f32_16x16x32_bf16 v[0:3], v[202:205], v[194:197], v[20:23]
	v_mfma_f32_16x16x32_bf16 v[16:19], v[206:209], v[198:201], v[0:3]
	v_mfma_f32_16x16x32_bf16 v[0:3], v[214:217], v[194:197], v[170:173]
	v_mfma_f32_16x16x32_bf16 v[20:23], v[218:221], v[198:201], v[0:3]
	v_mfma_f32_16x16x32_bf16 v[0:3], v[202:205], v[222:225], v[12:15]
	v_mfma_f32_16x16x32_bf16 v[8:11], v[206:209], v[226:229], v[0:3]
	v_mfma_f32_16x16x32_bf16 v[0:3], v[214:217], v[222:225], v[178:181]
	v_mfma_f32_16x16x32_bf16 v[12:15], v[218:221], v[226:229], v[0:3]
	v_mfma_f32_16x16x32_bf16 v[0:3], v[202:205], v[32:35], v[4:7]
	v_mfma_f32_16x16x32_bf16 v[4:7], v[214:217], v[32:35], v[142:145]
	v_mfma_f32_16x16x32_bf16 v[0:3], v[206:209], v[138:141], v[0:3]
	v_mfma_f32_16x16x32_bf16 v[4:7], v[218:221], v[138:141], v[4:7]
	s_setprio 0
	s_cmpk_lt_u32 s11, 0x100
	s_barrier
	s_cbranch_scc0 .LBB0_144
	s_barrier
